# v027 + proj GEMM k-loop with the same LDS-fragment prefetch schedule as the swiglu GEMM
# speedup vs baseline: 1.0468x; 1.0036x over previous
; template <class Epi>
; DI void gemm_phase(const bf16_t* A, const bf16_t* Bt, int K, int mtiles, int ntiles, const Epi& epi, char* smem) {
;     ...
;         const int grp = it / pg, rem = it - grp * pg;
;         const int gl = mcnt - grp * 4, gsz = gl < 4 ? gl : 4;
;         const int mt = mbeg + grp * 4 + rem % gsz, nt = rem / gsz;
;         const bf16_t* Ag = A + (size_t)(mt * 256 + srow) * K + skc;
;         const bf16_t* Bg = Bt + (size_t)(nt * 256 + srow) * K + skc;
;         float* sst = (float*)(smem + 2 * HALF_LDS) + (tcount & 1) * 512; ++tcount;
;         epi.prefetch(mt * 256, tid, sst);
;         u32x4 ra[4], rb[4];
; #pragma unroll
;         for (int i = 0; i < 4; ++i) { ra[i] = *(const u32x4*)(Ag + (size_t)(64 * i) * K); rb[i] = *(const u32x4*)(Bg + (size_t)(64 * i) * K); }
; #pragma unroll
;         for (int i = 0; i < 4; ++i) { *(u32x4*)(sA + (srow + 64 * i) * 72 + skc) = ra[i]; *(u32x4*)(sB + (srow + 64 * i) * 72 + skc) = rb[i]; }
; #pragma unroll
;         for (int i = 0; i < 4; ++i) { ra[i] = *(const u32x4*)(Ag + (size_t)(64 * i) * K + 64); rb[i] = *(const u32x4*)(Bg + (size_t)(64 * i) * K + 64); }
;         __syncthreads();
;         f32x16 acc[4][2];
; #pragma unroll
;         for (int a = 0; a < 4; ++a)
; #pragma unroll
;             for (int b = 0; b < 2; ++b)
; #pragma unroll
;                 for (int i = 0; i < 16; ++i) acc[a][b][i] = 0.f;
;         for (int kt = 0; kt < nk; ++kt) {
;             const int cur = kt & 1;
;             const bf16_t* a_ = sA + cur * 256 * 72 + (wr * 128 + r) * 72 + 8 * h;
;             const bf16_t* b_ = sB + cur * 256 * 72 + (wc * 64 + r) * 72 + 8 * h;
;             bf16_t* wa = sA + (cur ^ 1) * 256 * 72 + srow * 72 + skc; bf16_t* wb = sB + (cur ^ 1) * 256 * 72 + srow * 72 + skc;
;     ...
;             GEMM_KS(0) GEMM_KS(1)
;             __builtin_amdgcn_sched_barrier(0);
;             if (kt + 1 < nk) {
; #pragma unroll
;                 for (int i = 0; i < 4; ++i) *(u32x4*)(wa + 64 * i * 72) = ra[i];
;             }
;             if (kt + 2 < nk) {
; #pragma unroll
;                 for (int i = 0; i < 4; ++i) ra[i] = *(const u32x4*)(Ag + (size_t)(64 * i) * K + (kt + 2) * 64);
;             }
;             GEMM_KS(2)
;             __builtin_amdgcn_sched_barrier(0);
;             if (kt + 1 < nk) {
; #pragma unroll
;                 for (int i = 0; i < 4; ++i) *(u32x4*)(wb + 64 * i * 72) = rb[i];
;             }
.LBB0_316:
	s_mul_hi_i32 s0, s8, 0x2e8ba2e9
	s_lshr_b32 s1, s0, 31
	s_ashr_i32 s0, s0, 3
	s_add_i32 s0, s0, s1
	s_mul_i32 s1, s0, 0xffffffd4
	s_lshl_b32 s0, s0, 2
	s_sub_i32 s4, 33, s0
	s_min_u32 s4, s4, 4
	v_cvt_f32_ubyte0_e32 v0, s4
	v_rcp_iflag_f32_e32 v0, v0
	s_sub_i32 s7, 0, s4
	s_add_i32 s1, s8, s1
	s_abs_i32 s6, s1
	v_mul_f32_e32 v0, 0x4f7ffffe, v0
	v_cvt_u32_f32_e32 v0, v0
	s_ashr_i32 s5, s1, 31
	v_readfirstlane_b32 s11, v0
	s_mul_i32 s7, s7, s11
	s_mul_hi_u32 s7, s11, s7
	s_add_i32 s11, s11, s7
	s_mul_hi_u32 s7, s6, s11
	s_mul_i32 s11, s7, s4
	s_sub_i32 s6, s6, s11
	s_add_i32 s11, s7, 1
	s_sub_i32 s12, s6, s4
	s_cmp_ge_u32 s6, s4
	s_cselect_b32 s7, s11, s7
	s_cselect_b32 s6, s12, s6
	s_add_i32 s11, s7, 1
	s_cmp_ge_u32 s6, s4
	s_cselect_b32 s6, s11, s7
	s_xor_b32 s6, s6, s5
	s_sub_i32 s5, s6, s5
	s_mul_i32 s4, s5, s4
	s_sub_i32 s1, s1, s4
	s_add_i32 s1, s1, s10
	s_add_i32 s1, s1, s0
	s_lshl_b32 s4, s1, 8
	v_add_u32_e32 v0, s4, v152
	v_ashrrev_i32_e32 v1, 31, v0
	v_lshlrev_b64 v[0:1], 11, v[0:1]
	s_lshl_b32 s5, s5, 8
	v_lshl_add_u64 v[142:143], v[128:129], 0, v[0:1]
	v_add_u32_e32 v0, s5, v152
	v_ashrrev_i32_e32 v1, 31, v0
	s_mov_b32 s6, 0x20000
	v_lshlrev_b64 v[0:1], 11, v[0:1]
	v_add_co_u32_e64 v146, s[0:1], s6, v142
	v_lshl_add_u64 v[136:137], v[130:131], 0, v[0:1]
	s_nop 0
	v_addc_co_u32_e64 v147, s[0:1], 0, v143, s[0:1]
	v_add_co_u32_e64 v138, s[0:1], s6, v136
	global_load_dwordx4 v[0:3], v[142:143], off
	global_load_dwordx4 v[4:7], v[136:137], off
	v_addc_co_u32_e64 v139, s[0:1], 0, v137, s[0:1]
	v_add_co_u32_e64 v148, s[0:1], s15, v142
	global_load_dwordx4 v[8:11], v[146:147], off
	s_nop 0
	v_addc_co_u32_e64 v149, s[0:1], 0, v143, s[0:1]
	v_add_co_u32_e64 v140, s[0:1], s15, v136
	global_load_dwordx4 v[12:15], v[138:139], off
	s_nop 0
	v_addc_co_u32_e64 v141, s[0:1], 0, v137, s[0:1]
	v_add_co_u32_e64 v150, s[0:1], s16, v142
	global_load_dwordx4 v[16:19], v[148:149], off
	s_nop 0
	v_addc_co_u32_e64 v151, s[0:1], 0, v143, s[0:1]
	global_load_dwordx4 v[20:23], v[140:141], off
	v_add_co_u32_e64 v144, s[0:1], s16, v136
	global_load_dwordx4 v[24:27], v[150:151], off
	s_nop 0
	v_addc_co_u32_e64 v145, s[0:1], 0, v137, s[0:1]
	global_load_dwordx4 v[28:31], v[144:145], off
	s_waitcnt vmcnt(7)
	ds_write_b128 v156, v[0:3]
	s_waitcnt vmcnt(6)
	ds_write_b128 v157, v[4:7]
	s_waitcnt vmcnt(5)
	ds_write_b128 v156, v[8:11] offset:9216
	s_waitcnt vmcnt(4)
	ds_write_b128 v157, v[12:15] offset:9216
	s_waitcnt vmcnt(3)
	ds_write_b128 v156, v[16:19] offset:18432
	s_waitcnt vmcnt(2)
	ds_write_b128 v157, v[20:23] offset:18432
	s_waitcnt vmcnt(1)
	ds_write_b128 v156, v[24:27] offset:27648
	s_waitcnt vmcnt(0)
	ds_write_b128 v157, v[28:31] offset:27648
	global_load_dwordx4 v[170:173], v[142:143], off offset:128
	global_load_dwordx4 v[178:181], v[146:147], off offset:128
	global_load_dwordx4 v[186:189], v[148:149], off offset:128
	global_load_dwordx4 v[194:197], v[150:151], off offset:128
	global_load_dwordx4 v[174:177], v[136:137], off offset:128
	global_load_dwordx4 v[182:185], v[138:139], off offset:128
	global_load_dwordx4 v[190:193], v[140:141], off offset:128
	global_load_dwordx4 v[198:201], v[144:145], off offset:128
	s_waitcnt lgkmcnt(0)
	s_barrier
	ds_read_b128 v[202:205], v155
	ds_read_b128 v[240:243], v154 offset:4608
	ds_read_b128 v[206:209], v155 offset:4608
	ds_read_b128 v[244:247], v154 offset:9216
	ds_read_b128 v[248:251], v154 offset:13824
	ds_read_b128 v[210:213], v154
	s_waitcnt lgkmcnt(4)
	v_mfma_f32_32x32x16_bf16 v[96:111], v[240:243], v[202:205], 0
	ds_read_b128 v[214:217], v155 offset:32
	ds_read_b128 v[218:221], v155 offset:4640
	s_waitcnt lgkmcnt(5)
	v_mfma_f32_32x32x16_bf16 v[64:79], v[240:243], v[206:209], 0
	ds_read_b128 v[240:243], v154 offset:4640
	s_waitcnt lgkmcnt(5)
	v_mfma_f32_32x32x16_bf16 v[48:63], v[244:247], v[202:205], 0
	ds_read_b128 v[222:225], v154 offset:32
	v_mfma_f32_32x32x16_bf16 v[16:31], v[244:247], v[206:209], 0
	ds_read_b128 v[244:247], v154 offset:9248
	s_waitcnt lgkmcnt(6)
	v_mfma_f32_32x32x16_bf16 v[32:47], v[248:251], v[202:205], 0
	s_waitcnt vmcnt(7)
	ds_write_b128 v156, v[170:173] offset:36864
	global_load_dwordx4 v[170:173], v[142:143], off offset:256
	v_mfma_f32_32x32x16_bf16 v[0:15], v[248:251], v[206:209], 0
	ds_read_b128 v[248:251], v154 offset:13856
	s_waitcnt vmcnt(7)
	ds_write_b128 v156, v[178:181] offset:46080
	global_load_dwordx4 v[178:181], v[146:147], off offset:256
	s_waitcnt lgkmcnt(8)
	v_mfma_f32_32x32x16_bf16 v[112:127], v[210:213], v[202:205], 0
	s_waitcnt vmcnt(7)
	ds_write_b128 v156, v[186:189] offset:55296
	global_load_dwordx4 v[186:189], v[148:149], off offset:256
	v_mfma_f32_32x32x16_bf16 v[80:95], v[210:213], v[206:209], 0
	s_waitcnt vmcnt(7)
	ds_write_b128 v156, v[194:197] offset:64512
	global_load_dwordx4 v[194:197], v[150:151], off offset:256
	s_waitcnt lgkmcnt(7)
	v_mfma_f32_32x32x16_bf16 v[96:111], v[240:243], v[214:217], v[96:111]
	ds_read_b128 v[202:205], v155 offset:64
	ds_read_b128 v[206:209], v155 offset:4672
	v_mfma_f32_32x32x16_bf16 v[64:79], v[240:243], v[218:221], v[64:79]
	ds_read_b128 v[240:243], v154 offset:4672
	s_waitcnt lgkmcnt(8)
	v_mfma_f32_32x32x16_bf16 v[48:63], v[244:247], v[214:217], v[48:63]
	ds_read_b128 v[210:213], v154 offset:64
	v_mfma_f32_32x32x16_bf16 v[16:31], v[244:247], v[218:221], v[16:31]
	ds_read_b128 v[244:247], v154 offset:9280
	s_waitcnt lgkmcnt(8)
	v_mfma_f32_32x32x16_bf16 v[32:47], v[248:251], v[214:217], v[32:47]
	s_waitcnt vmcnt(7)
	ds_write_b128 v157, v[174:177] offset:36864
	global_load_dwordx4 v[174:177], v[136:137], off offset:256
	v_mfma_f32_32x32x16_bf16 v[0:15], v[248:251], v[218:221], v[0:15]
	ds_read_b128 v[248:251], v154 offset:13888
	s_waitcnt vmcnt(7)
; template <class Epi>
; DI void gemm_phase(const bf16_t* A, const bf16_t* Bt, int K, int mtiles, int ntiles, const Epi& epi, char* smem) {
;     ...
;         for (int kt = 0; kt < nk; ++kt) {
;             const int cur = kt & 1;
;             const bf16_t* a_ = sA + cur * 256 * 72 + (wr * 128 + r) * 72 + 8 * h;
;             const bf16_t* b_ = sB + cur * 256 * 72 + (wc * 64 + r) * 72 + 8 * h;
;             bf16_t* wa = sA + (cur ^ 1) * 256 * 72 + srow * 72 + skc; bf16_t* wb = sB + (cur ^ 1) * 256 * 72 + srow * 72 + skc;
;     ...
;             GEMM_KS(0) GEMM_KS(1)
;             __builtin_amdgcn_sched_barrier(0);
;             if (kt + 1 < nk) {
; #pragma unroll
;                 for (int i = 0; i < 4; ++i) *(u32x4*)(wa + 64 * i * 72) = ra[i];
;             }
;             if (kt + 2 < nk) {
; #pragma unroll
;                 for (int i = 0; i < 4; ++i) ra[i] = *(const u32x4*)(Ag + (size_t)(64 * i) * K + (kt + 2) * 64);
;             }
;             GEMM_KS(2)
;             __builtin_amdgcn_sched_barrier(0);
;             if (kt + 1 < nk) {
; #pragma unroll
;                 for (int i = 0; i < 4; ++i) *(u32x4*)(wb + 64 * i * 72) = rb[i];
;             }
;             if (kt + 2 < nk) {
; #pragma unroll
;                 for (int i = 0; i < 4; ++i) rb[i] = *(const u32x4*)(Bg + (size_t)(64 * i) * K + (kt + 2) * 64);
;             }
;             GEMM_KS(3)
;     ...
;             __syncthreads();
	ds_write_b128 v157, v[182:185] offset:46080
	global_load_dwordx4 v[182:185], v[138:139], off offset:256
	v_mfma_f32_32x32x16_bf16 v[112:127], v[222:225], v[214:217], v[112:127]
	s_waitcnt vmcnt(7)
	ds_write_b128 v157, v[190:193] offset:55296
	global_load_dwordx4 v[190:193], v[140:141], off offset:256
	v_mfma_f32_32x32x16_bf16 v[80:95], v[222:225], v[218:221], v[80:95]
	s_waitcnt vmcnt(7)
	ds_write_b128 v157, v[198:201] offset:64512
	global_load_dwordx4 v[198:201], v[144:145], off offset:256
	s_waitcnt lgkmcnt(7)
	v_mfma_f32_32x32x16_bf16 v[96:111], v[240:243], v[202:205], v[96:111]
	ds_read_b128 v[214:217], v155 offset:96
	ds_read_b128 v[218:221], v155 offset:4704
	v_mfma_f32_32x32x16_bf16 v[64:79], v[240:243], v[206:209], v[64:79]
	ds_read_b128 v[240:243], v154 offset:4704
	s_waitcnt lgkmcnt(8)
	v_mfma_f32_32x32x16_bf16 v[48:63], v[244:247], v[202:205], v[48:63]
	ds_read_b128 v[222:225], v154 offset:96
	v_mfma_f32_32x32x16_bf16 v[16:31], v[244:247], v[206:209], v[16:31]
	ds_read_b128 v[244:247], v154 offset:9312
	s_waitcnt lgkmcnt(8)
	v_mfma_f32_32x32x16_bf16 v[32:47], v[248:251], v[202:205], v[32:47]
	v_mfma_f32_32x32x16_bf16 v[0:15], v[248:251], v[206:209], v[0:15]
	ds_read_b128 v[248:251], v154 offset:13920
	v_mfma_f32_32x32x16_bf16 v[112:127], v[210:213], v[202:205], v[112:127]
	v_mfma_f32_32x32x16_bf16 v[80:95], v[210:213], v[206:209], v[80:95]
	s_waitcnt lgkmcnt(0)
	s_barrier
	v_mfma_f32_32x32x16_bf16 v[96:111], v[240:243], v[214:217], v[96:111]
	ds_read_b128 v[202:205], v155 offset:36864
	ds_read_b128 v[206:209], v155 offset:41472
	v_mfma_f32_32x32x16_bf16 v[64:79], v[240:243], v[218:221], v[64:79]
	ds_read_b128 v[240:243], v154 offset:41472
	v_mfma_f32_32x32x16_bf16 v[48:63], v[244:247], v[214:217], v[48:63]
	ds_read_b128 v[210:213], v154 offset:36864
	v_mfma_f32_32x32x16_bf16 v[16:31], v[244:247], v[218:221], v[16:31]
	ds_read_b128 v[244:247], v154 offset:46080
	v_mfma_f32_32x32x16_bf16 v[32:47], v[248:251], v[214:217], v[32:47]
	v_mfma_f32_32x32x16_bf16 v[0:15], v[248:251], v[218:221], v[0:15]
	ds_read_b128 v[248:251], v154 offset:50688
	v_mfma_f32_32x32x16_bf16 v[112:127], v[222:225], v[214:217], v[112:127]
	v_mfma_f32_32x32x16_bf16 v[80:95], v[222:225], v[218:221], v[80:95]
	s_waitcnt lgkmcnt(3)
	v_mfma_f32_32x32x16_bf16 v[96:111], v[240:243], v[202:205], v[96:111]
	ds_read_b128 v[214:217], v155 offset:36896
	ds_read_b128 v[218:221], v155 offset:41504
	v_mfma_f32_32x32x16_bf16 v[64:79], v[240:243], v[206:209], v[64:79]
	ds_read_b128 v[240:243], v154 offset:41504
	s_waitcnt lgkmcnt(4)
	v_mfma_f32_32x32x16_bf16 v[48:63], v[244:247], v[202:205], v[48:63]
	ds_read_b128 v[222:225], v154 offset:36896
	v_mfma_f32_32x32x16_bf16 v[16:31], v[244:247], v[206:209], v[16:31]
	ds_read_b128 v[244:247], v154 offset:46112
	s_waitcnt lgkmcnt(5)
	v_mfma_f32_32x32x16_bf16 v[32:47], v[248:251], v[202:205], v[32:47]
	s_waitcnt vmcnt(7)
	ds_write_b128 v156, v[170:173] offset:0
	global_load_dwordx4 v[170:173], v[142:143], off offset:384
	v_mfma_f32_32x32x16_bf16 v[0:15], v[248:251], v[206:209], v[0:15]
	ds_read_b128 v[248:251], v154 offset:50720
	s_waitcnt vmcnt(7)
	ds_write_b128 v156, v[178:181] offset:9216
	global_load_dwordx4 v[178:181], v[146:147], off offset:384
	v_mfma_f32_32x32x16_bf16 v[112:127], v[210:213], v[202:205], v[112:127]
	s_waitcnt vmcnt(7)
	ds_write_b128 v156, v[186:189] offset:18432
	global_load_dwordx4 v[186:189], v[148:149], off offset:384
	v_mfma_f32_32x32x16_bf16 v[80:95], v[210:213], v[206:209], v[80:95]
	s_waitcnt vmcnt(7)
	ds_write_b128 v156, v[194:197] offset:27648
	global_load_dwordx4 v[194:197], v[150:151], off offset:384
	s_waitcnt lgkmcnt(7)
	v_mfma_f32_32x32x16_bf16 v[96:111], v[240:243], v[214:217], v[96:111]
	ds_read_b128 v[202:205], v155 offset:36928
	ds_read_b128 v[206:209], v155 offset:41536
	v_mfma_f32_32x32x16_bf16 v[64:79], v[240:243], v[218:221], v[64:79]
	ds_read_b128 v[240:243], v154 offset:41536
	s_waitcnt lgkmcnt(8)
	v_mfma_f32_32x32x16_bf16 v[48:63], v[244:247], v[214:217], v[48:63]
	ds_read_b128 v[210:213], v154 offset:36928
	v_mfma_f32_32x32x16_bf16 v[16:31], v[244:247], v[218:221], v[16:31]
	ds_read_b128 v[244:247], v154 offset:46144
	s_waitcnt lgkmcnt(8)
	v_mfma_f32_32x32x16_bf16 v[32:47], v[248:251], v[214:217], v[32:47]
	s_waitcnt vmcnt(7)
	ds_write_b128 v157, v[174:177] offset:0
	global_load_dwordx4 v[174:177], v[136:137], off offset:384
	v_mfma_f32_32x32x16_bf16 v[0:15], v[248:251], v[218:221], v[0:15]
	ds_read_b128 v[248:251], v154 offset:50752
	s_waitcnt vmcnt(7)
	ds_write_b128 v157, v[182:185] offset:9216
	global_load_dwordx4 v[182:185], v[138:139], off offset:384
	v_mfma_f32_32x32x16_bf16 v[112:127], v[222:225], v[214:217], v[112:127]
	s_waitcnt vmcnt(7)
	ds_write_b128 v157, v[190:193] offset:18432
	global_load_dwordx4 v[190:193], v[140:141], off offset:384
	v_mfma_f32_32x32x16_bf16 v[80:95], v[222:225], v[218:221], v[80:95]
	s_waitcnt vmcnt(7)
	ds_write_b128 v157, v[198:201] offset:27648
	global_load_dwordx4 v[198:201], v[144:145], off offset:384
	s_waitcnt lgkmcnt(7)
	v_mfma_f32_32x32x16_bf16 v[96:111], v[240:243], v[202:205], v[96:111]
	ds_read_b128 v[214:217], v155 offset:36960
	ds_read_b128 v[218:221], v155 offset:41568
	v_mfma_f32_32x32x16_bf16 v[64:79], v[240:243], v[206:209], v[64:79]
	ds_read_b128 v[240:243], v154 offset:41568
	s_waitcnt lgkmcnt(8)
	v_mfma_f32_32x32x16_bf16 v[48:63], v[244:247], v[202:205], v[48:63]
	ds_read_b128 v[222:225], v154 offset:36960
	v_mfma_f32_32x32x16_bf16 v[16:31], v[244:247], v[206:209], v[16:31]
	ds_read_b128 v[244:247], v154 offset:46176
	s_waitcnt lgkmcnt(8)
	v_mfma_f32_32x32x16_bf16 v[32:47], v[248:251], v[202:205], v[32:47]
	v_mfma_f32_32x32x16_bf16 v[0:15], v[248:251], v[206:209], v[0:15]
	ds_read_b128 v[248:251], v154 offset:50784
	v_mfma_f32_32x32x16_bf16 v[112:127], v[210:213], v[202:205], v[112:127]
	v_mfma_f32_32x32x16_bf16 v[80:95], v[210:213], v[206:209], v[80:95]
	s_waitcnt lgkmcnt(0)
	s_barrier
; template <class Epi>
; DI void gemm_phase(const bf16_t* A, const bf16_t* Bt, int K, int mtiles, int ntiles, const Epi& epi, char* smem) {
;     ...
;         for (int kt = 0; kt < nk; ++kt) {
;             const int cur = kt & 1;
;             const bf16_t* a_ = sA + cur * 256 * 72 + (wr * 128 + r) * 72 + 8 * h;
;             const bf16_t* b_ = sB + cur * 256 * 72 + (wc * 64 + r) * 72 + 8 * h;
;             bf16_t* wa = sA + (cur ^ 1) * 256 * 72 + srow * 72 + skc; bf16_t* wb = sB + (cur ^ 1) * 256 * 72 + srow * 72 + skc;
;     ...
;             GEMM_KS(0) GEMM_KS(1)
;             __builtin_amdgcn_sched_barrier(0);
;             if (kt + 1 < nk) {
; #pragma unroll
;                 for (int i = 0; i < 4; ++i) *(u32x4*)(wa + 64 * i * 72) = ra[i];
;             }
;             if (kt + 2 < nk) {
; #pragma unroll
;                 for (int i = 0; i < 4; ++i) ra[i] = *(const u32x4*)(Ag + (size_t)(64 * i) * K + (kt + 2) * 64);
;             }
;             GEMM_KS(2)
;             __builtin_amdgcn_sched_barrier(0);
;             if (kt + 1 < nk) {
; #pragma unroll
;                 for (int i = 0; i < 4; ++i) *(u32x4*)(wb + 64 * i * 72) = rb[i];
;             }
;             if (kt + 2 < nk) {
; #pragma unroll
;                 for (int i = 0; i < 4; ++i) rb[i] = *(const u32x4*)(Bg + (size_t)(64 * i) * K + (kt + 2) * 64);
;             }
;             GEMM_KS(3)
;     ...
;             __syncthreads();
	v_mfma_f32_32x32x16_bf16 v[96:111], v[240:243], v[214:217], v[96:111]
	ds_read_b128 v[202:205], v155
	ds_read_b128 v[206:209], v155 offset:4608
	v_mfma_f32_32x32x16_bf16 v[64:79], v[240:243], v[218:221], v[64:79]
	ds_read_b128 v[240:243], v154 offset:4608
	v_mfma_f32_32x32x16_bf16 v[48:63], v[244:247], v[214:217], v[48:63]
	ds_read_b128 v[210:213], v154
	v_mfma_f32_32x32x16_bf16 v[16:31], v[244:247], v[218:221], v[16:31]
	ds_read_b128 v[244:247], v154 offset:9216
	v_mfma_f32_32x32x16_bf16 v[32:47], v[248:251], v[214:217], v[32:47]
	v_mfma_f32_32x32x16_bf16 v[0:15], v[248:251], v[218:221], v[0:15]
	ds_read_b128 v[248:251], v154 offset:13824
	v_mfma_f32_32x32x16_bf16 v[112:127], v[222:225], v[214:217], v[112:127]
	v_mfma_f32_32x32x16_bf16 v[80:95], v[222:225], v[218:221], v[80:95]
	s_waitcnt lgkmcnt(3)
	v_mfma_f32_32x32x16_bf16 v[96:111], v[240:243], v[202:205], v[96:111]
	ds_read_b128 v[214:217], v155 offset:32
	ds_read_b128 v[218:221], v155 offset:4640
	v_mfma_f32_32x32x16_bf16 v[64:79], v[240:243], v[206:209], v[64:79]
	ds_read_b128 v[240:243], v154 offset:4640
	s_waitcnt lgkmcnt(4)
	v_mfma_f32_32x32x16_bf16 v[48:63], v[244:247], v[202:205], v[48:63]
	ds_read_b128 v[222:225], v154 offset:32
	v_mfma_f32_32x32x16_bf16 v[16:31], v[244:247], v[206:209], v[16:31]
	ds_read_b128 v[244:247], v154 offset:9248
	s_waitcnt lgkmcnt(5)
	v_mfma_f32_32x32x16_bf16 v[32:47], v[248:251], v[202:205], v[32:47]
	s_waitcnt vmcnt(7)
	ds_write_b128 v156, v[170:173] offset:36864
	global_load_dwordx4 v[170:173], v[142:143], off offset:512
	v_mfma_f32_32x32x16_bf16 v[0:15], v[248:251], v[206:209], v[0:15]
	ds_read_b128 v[248:251], v154 offset:13856
	s_waitcnt vmcnt(7)
	ds_write_b128 v156, v[178:181] offset:46080
	global_load_dwordx4 v[178:181], v[146:147], off offset:512
	v_mfma_f32_32x32x16_bf16 v[112:127], v[210:213], v[202:205], v[112:127]
	s_waitcnt vmcnt(7)
	ds_write_b128 v156, v[186:189] offset:55296
	global_load_dwordx4 v[186:189], v[148:149], off offset:512
	v_mfma_f32_32x32x16_bf16 v[80:95], v[210:213], v[206:209], v[80:95]
	s_waitcnt vmcnt(7)
	ds_write_b128 v156, v[194:197] offset:64512
	global_load_dwordx4 v[194:197], v[150:151], off offset:512
	s_waitcnt lgkmcnt(7)
	v_mfma_f32_32x32x16_bf16 v[96:111], v[240:243], v[214:217], v[96:111]
	ds_read_b128 v[202:205], v155 offset:64
	ds_read_b128 v[206:209], v155 offset:4672
	v_mfma_f32_32x32x16_bf16 v[64:79], v[240:243], v[218:221], v[64:79]
	ds_read_b128 v[240:243], v154 offset:4672
	s_waitcnt lgkmcnt(8)
	v_mfma_f32_32x32x16_bf16 v[48:63], v[244:247], v[214:217], v[48:63]
	ds_read_b128 v[210:213], v154 offset:64
	v_mfma_f32_32x32x16_bf16 v[16:31], v[244:247], v[218:221], v[16:31]
	ds_read_b128 v[244:247], v154 offset:9280
	s_waitcnt lgkmcnt(8)
	v_mfma_f32_32x32x16_bf16 v[32:47], v[248:251], v[214:217], v[32:47]
	s_waitcnt vmcnt(7)
	ds_write_b128 v157, v[174:177] offset:36864
	global_load_dwordx4 v[174:177], v[136:137], off offset:512
	v_mfma_f32_32x32x16_bf16 v[0:15], v[248:251], v[218:221], v[0:15]
	ds_read_b128 v[248:251], v154 offset:13888
	s_waitcnt vmcnt(7)
	ds_write_b128 v157, v[182:185] offset:46080
	global_load_dwordx4 v[182:185], v[138:139], off offset:512
	v_mfma_f32_32x32x16_bf16 v[112:127], v[222:225], v[214:217], v[112:127]
	s_waitcnt vmcnt(7)
	ds_write_b128 v157, v[190:193] offset:55296
	global_load_dwordx4 v[190:193], v[140:141], off offset:512
	v_mfma_f32_32x32x16_bf16 v[80:95], v[222:225], v[218:221], v[80:95]
	s_waitcnt vmcnt(7)
	ds_write_b128 v157, v[198:201] offset:64512
	global_load_dwordx4 v[198:201], v[144:145], off offset:512
	s_waitcnt lgkmcnt(7)
	v_mfma_f32_32x32x16_bf16 v[96:111], v[240:243], v[202:205], v[96:111]
	ds_read_b128 v[214:217], v155 offset:96
	ds_read_b128 v[218:221], v155 offset:4704
	v_mfma_f32_32x32x16_bf16 v[64:79], v[240:243], v[206:209], v[64:79]
	ds_read_b128 v[240:243], v154 offset:4704
	s_waitcnt lgkmcnt(8)
	v_mfma_f32_32x32x16_bf16 v[48:63], v[244:247], v[202:205], v[48:63]
	ds_read_b128 v[222:225], v154 offset:96
	v_mfma_f32_32x32x16_bf16 v[16:31], v[244:247], v[206:209], v[16:31]
	ds_read_b128 v[244:247], v154 offset:9312
	s_waitcnt lgkmcnt(8)
	v_mfma_f32_32x32x16_bf16 v[32:47], v[248:251], v[202:205], v[32:47]
	v_mfma_f32_32x32x16_bf16 v[0:15], v[248:251], v[206:209], v[0:15]
	ds_read_b128 v[248:251], v154 offset:13920
	v_mfma_f32_32x32x16_bf16 v[112:127], v[210:213], v[202:205], v[112:127]
	v_mfma_f32_32x32x16_bf16 v[80:95], v[210:213], v[206:209], v[80:95]
	s_waitcnt lgkmcnt(0)
	s_barrier
; template <class Epi>
; DI void gemm_phase(const bf16_t* A, const bf16_t* Bt, int K, int mtiles, int ntiles, const Epi& epi, char* smem) {
;     ...
;         for (int kt = 0; kt < nk; ++kt) {
;             const int cur = kt & 1;
;             const bf16_t* a_ = sA + cur * 256 * 72 + (wr * 128 + r) * 72 + 8 * h;
;             const bf16_t* b_ = sB + cur * 256 * 72 + (wc * 64 + r) * 72 + 8 * h;
;             bf16_t* wa = sA + (cur ^ 1) * 256 * 72 + srow * 72 + skc; bf16_t* wb = sB + (cur ^ 1) * 256 * 72 + srow * 72 + skc;
;     ...
;             GEMM_KS(0) GEMM_KS(1)
;             __builtin_amdgcn_sched_barrier(0);
;             if (kt + 1 < nk) {
; #pragma unroll
;                 for (int i = 0; i < 4; ++i) *(u32x4*)(wa + 64 * i * 72) = ra[i];
;             }
;             if (kt + 2 < nk) {
; #pragma unroll
;                 for (int i = 0; i < 4; ++i) ra[i] = *(const u32x4*)(Ag + (size_t)(64 * i) * K + (kt + 2) * 64);
;             }
;             GEMM_KS(2)
;             __builtin_amdgcn_sched_barrier(0);
;             if (kt + 1 < nk) {
; #pragma unroll
;                 for (int i = 0; i < 4; ++i) *(u32x4*)(wb + 64 * i * 72) = rb[i];
;             }
;             if (kt + 2 < nk) {
; #pragma unroll
;                 for (int i = 0; i < 4; ++i) rb[i] = *(const u32x4*)(Bg + (size_t)(64 * i) * K + (kt + 2) * 64);
;             }
;             GEMM_KS(3)
;     ...
;             __syncthreads();
	v_mfma_f32_32x32x16_bf16 v[96:111], v[240:243], v[214:217], v[96:111]
	ds_read_b128 v[202:205], v155 offset:36864
	ds_read_b128 v[206:209], v155 offset:41472
	v_mfma_f32_32x32x16_bf16 v[64:79], v[240:243], v[218:221], v[64:79]
	ds_read_b128 v[240:243], v154 offset:41472
	v_mfma_f32_32x32x16_bf16 v[48:63], v[244:247], v[214:217], v[48:63]
	ds_read_b128 v[210:213], v154 offset:36864
	v_mfma_f32_32x32x16_bf16 v[16:31], v[244:247], v[218:221], v[16:31]
	ds_read_b128 v[244:247], v154 offset:46080
	v_mfma_f32_32x32x16_bf16 v[32:47], v[248:251], v[214:217], v[32:47]
	v_mfma_f32_32x32x16_bf16 v[0:15], v[248:251], v[218:221], v[0:15]
	ds_read_b128 v[248:251], v154 offset:50688
	v_mfma_f32_32x32x16_bf16 v[112:127], v[222:225], v[214:217], v[112:127]
	v_mfma_f32_32x32x16_bf16 v[80:95], v[222:225], v[218:221], v[80:95]
	s_waitcnt lgkmcnt(3)
	v_mfma_f32_32x32x16_bf16 v[96:111], v[240:243], v[202:205], v[96:111]
	ds_read_b128 v[214:217], v155 offset:36896
	ds_read_b128 v[218:221], v155 offset:41504
	v_mfma_f32_32x32x16_bf16 v[64:79], v[240:243], v[206:209], v[64:79]
	ds_read_b128 v[240:243], v154 offset:41504
	s_waitcnt lgkmcnt(4)
	v_mfma_f32_32x32x16_bf16 v[48:63], v[244:247], v[202:205], v[48:63]
	ds_read_b128 v[222:225], v154 offset:36896
	v_mfma_f32_32x32x16_bf16 v[16:31], v[244:247], v[206:209], v[16:31]
	ds_read_b128 v[244:247], v154 offset:46112
	s_waitcnt lgkmcnt(5)
	v_mfma_f32_32x32x16_bf16 v[32:47], v[248:251], v[202:205], v[32:47]
	s_waitcnt vmcnt(7)
	ds_write_b128 v156, v[170:173] offset:0
	global_load_dwordx4 v[170:173], v[142:143], off offset:640
	v_mfma_f32_32x32x16_bf16 v[0:15], v[248:251], v[206:209], v[0:15]
	ds_read_b128 v[248:251], v154 offset:50720
	s_waitcnt vmcnt(7)
	ds_write_b128 v156, v[178:181] offset:9216
	global_load_dwordx4 v[178:181], v[146:147], off offset:640
	v_mfma_f32_32x32x16_bf16 v[112:127], v[210:213], v[202:205], v[112:127]
	s_waitcnt vmcnt(7)
	ds_write_b128 v156, v[186:189] offset:18432
	global_load_dwordx4 v[186:189], v[148:149], off offset:640
	v_mfma_f32_32x32x16_bf16 v[80:95], v[210:213], v[206:209], v[80:95]
	s_waitcnt vmcnt(7)
	ds_write_b128 v156, v[194:197] offset:27648
	global_load_dwordx4 v[194:197], v[150:151], off offset:640
	s_waitcnt lgkmcnt(7)
	v_mfma_f32_32x32x16_bf16 v[96:111], v[240:243], v[214:217], v[96:111]
	ds_read_b128 v[202:205], v155 offset:36928
	ds_read_b128 v[206:209], v155 offset:41536
	v_mfma_f32_32x32x16_bf16 v[64:79], v[240:243], v[218:221], v[64:79]
	ds_read_b128 v[240:243], v154 offset:41536
	s_waitcnt lgkmcnt(8)
	v_mfma_f32_32x32x16_bf16 v[48:63], v[244:247], v[214:217], v[48:63]
	ds_read_b128 v[210:213], v154 offset:36928
	v_mfma_f32_32x32x16_bf16 v[16:31], v[244:247], v[218:221], v[16:31]
	ds_read_b128 v[244:247], v154 offset:46144
	s_waitcnt lgkmcnt(8)
	v_mfma_f32_32x32x16_bf16 v[32:47], v[248:251], v[214:217], v[32:47]
	s_waitcnt vmcnt(7)
	ds_write_b128 v157, v[174:177] offset:0
	global_load_dwordx4 v[174:177], v[136:137], off offset:640
	v_mfma_f32_32x32x16_bf16 v[0:15], v[248:251], v[218:221], v[0:15]
	ds_read_b128 v[248:251], v154 offset:50752
	s_waitcnt vmcnt(7)
	ds_write_b128 v157, v[182:185] offset:9216
	global_load_dwordx4 v[182:185], v[138:139], off offset:640
	v_mfma_f32_32x32x16_bf16 v[112:127], v[222:225], v[214:217], v[112:127]
	s_waitcnt vmcnt(7)
	ds_write_b128 v157, v[190:193] offset:18432
	global_load_dwordx4 v[190:193], v[140:141], off offset:640
	v_mfma_f32_32x32x16_bf16 v[80:95], v[222:225], v[218:221], v[80:95]
	s_waitcnt vmcnt(7)
	ds_write_b128 v157, v[198:201] offset:27648
	global_load_dwordx4 v[198:201], v[144:145], off offset:640
	s_waitcnt lgkmcnt(7)
	v_mfma_f32_32x32x16_bf16 v[96:111], v[240:243], v[202:205], v[96:111]
	ds_read_b128 v[214:217], v155 offset:36960
	ds_read_b128 v[218:221], v155 offset:41568
	v_mfma_f32_32x32x16_bf16 v[64:79], v[240:243], v[206:209], v[64:79]
	ds_read_b128 v[240:243], v154 offset:41568
	s_waitcnt lgkmcnt(8)
	v_mfma_f32_32x32x16_bf16 v[48:63], v[244:247], v[202:205], v[48:63]
	ds_read_b128 v[222:225], v154 offset:36960
	v_mfma_f32_32x32x16_bf16 v[16:31], v[244:247], v[206:209], v[16:31]
	ds_read_b128 v[244:247], v154 offset:46176
	s_waitcnt lgkmcnt(8)
	v_mfma_f32_32x32x16_bf16 v[32:47], v[248:251], v[202:205], v[32:47]
	v_mfma_f32_32x32x16_bf16 v[0:15], v[248:251], v[206:209], v[0:15]
	ds_read_b128 v[248:251], v154 offset:50784
	v_mfma_f32_32x32x16_bf16 v[112:127], v[210:213], v[202:205], v[112:127]
	v_mfma_f32_32x32x16_bf16 v[80:95], v[210:213], v[206:209], v[80:95]
	s_waitcnt lgkmcnt(0)
	s_barrier
; template <class Epi>
; DI void gemm_phase(const bf16_t* A, const bf16_t* Bt, int K, int mtiles, int ntiles, const Epi& epi, char* smem) {
;     ...
;         for (int kt = 0; kt < nk; ++kt) {
;             const int cur = kt & 1;
;             const bf16_t* a_ = sA + cur * 256 * 72 + (wr * 128 + r) * 72 + 8 * h;
;             const bf16_t* b_ = sB + cur * 256 * 72 + (wc * 64 + r) * 72 + 8 * h;
;             bf16_t* wa = sA + (cur ^ 1) * 256 * 72 + srow * 72 + skc; bf16_t* wb = sB + (cur ^ 1) * 256 * 72 + srow * 72 + skc;
;     ...
;             GEMM_KS(0) GEMM_KS(1)
;             __builtin_amdgcn_sched_barrier(0);
;             if (kt + 1 < nk) {
; #pragma unroll
;                 for (int i = 0; i < 4; ++i) *(u32x4*)(wa + 64 * i * 72) = ra[i];
;             }
;             if (kt + 2 < nk) {
; #pragma unroll
;                 for (int i = 0; i < 4; ++i) ra[i] = *(const u32x4*)(Ag + (size_t)(64 * i) * K + (kt + 2) * 64);
;             }
;             GEMM_KS(2)
;             __builtin_amdgcn_sched_barrier(0);
;             if (kt + 1 < nk) {
; #pragma unroll
;                 for (int i = 0; i < 4; ++i) *(u32x4*)(wb + 64 * i * 72) = rb[i];
;             }
;             if (kt + 2 < nk) {
; #pragma unroll
;                 for (int i = 0; i < 4; ++i) rb[i] = *(const u32x4*)(Bg + (size_t)(64 * i) * K + (kt + 2) * 64);
;             }
;             GEMM_KS(3)
;     ...
;             __syncthreads();
	v_mfma_f32_32x32x16_bf16 v[96:111], v[240:243], v[214:217], v[96:111]
	ds_read_b128 v[202:205], v155
	ds_read_b128 v[206:209], v155 offset:4608
	v_mfma_f32_32x32x16_bf16 v[64:79], v[240:243], v[218:221], v[64:79]
	ds_read_b128 v[240:243], v154 offset:4608
	v_mfma_f32_32x32x16_bf16 v[48:63], v[244:247], v[214:217], v[48:63]
	ds_read_b128 v[210:213], v154
	v_mfma_f32_32x32x16_bf16 v[16:31], v[244:247], v[218:221], v[16:31]
	ds_read_b128 v[244:247], v154 offset:9216
	v_mfma_f32_32x32x16_bf16 v[32:47], v[248:251], v[214:217], v[32:47]
	v_mfma_f32_32x32x16_bf16 v[0:15], v[248:251], v[218:221], v[0:15]
	ds_read_b128 v[248:251], v154 offset:13824
	v_mfma_f32_32x32x16_bf16 v[112:127], v[222:225], v[214:217], v[112:127]
	v_mfma_f32_32x32x16_bf16 v[80:95], v[222:225], v[218:221], v[80:95]
	s_waitcnt lgkmcnt(3)
	v_mfma_f32_32x32x16_bf16 v[96:111], v[240:243], v[202:205], v[96:111]
	ds_read_b128 v[214:217], v155 offset:32
	ds_read_b128 v[218:221], v155 offset:4640
	v_mfma_f32_32x32x16_bf16 v[64:79], v[240:243], v[206:209], v[64:79]
	ds_read_b128 v[240:243], v154 offset:4640
	s_waitcnt lgkmcnt(4)
	v_mfma_f32_32x32x16_bf16 v[48:63], v[244:247], v[202:205], v[48:63]
	ds_read_b128 v[222:225], v154 offset:32
	v_mfma_f32_32x32x16_bf16 v[16:31], v[244:247], v[206:209], v[16:31]
	ds_read_b128 v[244:247], v154 offset:9248
	s_waitcnt lgkmcnt(5)
	v_mfma_f32_32x32x16_bf16 v[32:47], v[248:251], v[202:205], v[32:47]
	s_waitcnt vmcnt(7)
	ds_write_b128 v156, v[170:173] offset:36864
	global_load_dwordx4 v[170:173], v[142:143], off offset:768
	v_mfma_f32_32x32x16_bf16 v[0:15], v[248:251], v[206:209], v[0:15]
	ds_read_b128 v[248:251], v154 offset:13856
	s_waitcnt vmcnt(7)
	ds_write_b128 v156, v[178:181] offset:46080
	global_load_dwordx4 v[178:181], v[146:147], off offset:768
	v_mfma_f32_32x32x16_bf16 v[112:127], v[210:213], v[202:205], v[112:127]
	s_waitcnt vmcnt(7)
	ds_write_b128 v156, v[186:189] offset:55296
	global_load_dwordx4 v[186:189], v[148:149], off offset:768
	v_mfma_f32_32x32x16_bf16 v[80:95], v[210:213], v[206:209], v[80:95]
	s_waitcnt vmcnt(7)
	ds_write_b128 v156, v[194:197] offset:64512
	global_load_dwordx4 v[194:197], v[150:151], off offset:768
	s_waitcnt lgkmcnt(7)
	v_mfma_f32_32x32x16_bf16 v[96:111], v[240:243], v[214:217], v[96:111]
	ds_read_b128 v[202:205], v155 offset:64
	ds_read_b128 v[206:209], v155 offset:4672
	v_mfma_f32_32x32x16_bf16 v[64:79], v[240:243], v[218:221], v[64:79]
	ds_read_b128 v[240:243], v154 offset:4672
	s_waitcnt lgkmcnt(8)
	v_mfma_f32_32x32x16_bf16 v[48:63], v[244:247], v[214:217], v[48:63]
	ds_read_b128 v[210:213], v154 offset:64
	v_mfma_f32_32x32x16_bf16 v[16:31], v[244:247], v[218:221], v[16:31]
	ds_read_b128 v[244:247], v154 offset:9280
	s_waitcnt lgkmcnt(8)
	v_mfma_f32_32x32x16_bf16 v[32:47], v[248:251], v[214:217], v[32:47]
	s_waitcnt vmcnt(7)
	ds_write_b128 v157, v[174:177] offset:36864
	global_load_dwordx4 v[174:177], v[136:137], off offset:768
	v_mfma_f32_32x32x16_bf16 v[0:15], v[248:251], v[218:221], v[0:15]
	ds_read_b128 v[248:251], v154 offset:13888
	s_waitcnt vmcnt(7)
	ds_write_b128 v157, v[182:185] offset:46080
	global_load_dwordx4 v[182:185], v[138:139], off offset:768
	v_mfma_f32_32x32x16_bf16 v[112:127], v[222:225], v[214:217], v[112:127]
	s_waitcnt vmcnt(7)
	ds_write_b128 v157, v[190:193] offset:55296
	global_load_dwordx4 v[190:193], v[140:141], off offset:768
	v_mfma_f32_32x32x16_bf16 v[80:95], v[222:225], v[218:221], v[80:95]
	s_waitcnt vmcnt(7)
	ds_write_b128 v157, v[198:201] offset:64512
	global_load_dwordx4 v[198:201], v[144:145], off offset:768
	s_waitcnt lgkmcnt(7)
	v_mfma_f32_32x32x16_bf16 v[96:111], v[240:243], v[202:205], v[96:111]
	ds_read_b128 v[214:217], v155 offset:96
	ds_read_b128 v[218:221], v155 offset:4704
	v_mfma_f32_32x32x16_bf16 v[64:79], v[240:243], v[206:209], v[64:79]
	ds_read_b128 v[240:243], v154 offset:4704
	s_waitcnt lgkmcnt(8)
	v_mfma_f32_32x32x16_bf16 v[48:63], v[244:247], v[202:205], v[48:63]
	ds_read_b128 v[222:225], v154 offset:96
	v_mfma_f32_32x32x16_bf16 v[16:31], v[244:247], v[206:209], v[16:31]
	ds_read_b128 v[244:247], v154 offset:9312
	s_waitcnt lgkmcnt(8)
	v_mfma_f32_32x32x16_bf16 v[32:47], v[248:251], v[202:205], v[32:47]
	v_mfma_f32_32x32x16_bf16 v[0:15], v[248:251], v[206:209], v[0:15]
	ds_read_b128 v[248:251], v154 offset:13920
	v_mfma_f32_32x32x16_bf16 v[112:127], v[210:213], v[202:205], v[112:127]
	v_mfma_f32_32x32x16_bf16 v[80:95], v[210:213], v[206:209], v[80:95]
	s_waitcnt lgkmcnt(0)
	s_barrier
; template <class Epi>
; DI void gemm_phase(const bf16_t* A, const bf16_t* Bt, int K, int mtiles, int ntiles, const Epi& epi, char* smem) {
;     ...
;         for (int kt = 0; kt < nk; ++kt) {
;             const int cur = kt & 1;
;             const bf16_t* a_ = sA + cur * 256 * 72 + (wr * 128 + r) * 72 + 8 * h;
;             const bf16_t* b_ = sB + cur * 256 * 72 + (wc * 64 + r) * 72 + 8 * h;
;             bf16_t* wa = sA + (cur ^ 1) * 256 * 72 + srow * 72 + skc; bf16_t* wb = sB + (cur ^ 1) * 256 * 72 + srow * 72 + skc;
;     ...
;             GEMM_KS(0) GEMM_KS(1)
;             __builtin_amdgcn_sched_barrier(0);
;             if (kt + 1 < nk) {
; #pragma unroll
;                 for (int i = 0; i < 4; ++i) *(u32x4*)(wa + 64 * i * 72) = ra[i];
;             }
;             if (kt + 2 < nk) {
; #pragma unroll
;                 for (int i = 0; i < 4; ++i) ra[i] = *(const u32x4*)(Ag + (size_t)(64 * i) * K + (kt + 2) * 64);
;             }
;             GEMM_KS(2)
;             __builtin_amdgcn_sched_barrier(0);
;             if (kt + 1 < nk) {
; #pragma unroll
;                 for (int i = 0; i < 4; ++i) *(u32x4*)(wb + 64 * i * 72) = rb[i];
;             }
;             if (kt + 2 < nk) {
; #pragma unroll
;                 for (int i = 0; i < 4; ++i) rb[i] = *(const u32x4*)(Bg + (size_t)(64 * i) * K + (kt + 2) * 64);
;             }
;             GEMM_KS(3)
;     ...
;             __syncthreads();
	v_mfma_f32_32x32x16_bf16 v[96:111], v[240:243], v[214:217], v[96:111]
	ds_read_b128 v[202:205], v155 offset:36864
	ds_read_b128 v[206:209], v155 offset:41472
	v_mfma_f32_32x32x16_bf16 v[64:79], v[240:243], v[218:221], v[64:79]
	ds_read_b128 v[240:243], v154 offset:41472
	v_mfma_f32_32x32x16_bf16 v[48:63], v[244:247], v[214:217], v[48:63]
	ds_read_b128 v[210:213], v154 offset:36864
	v_mfma_f32_32x32x16_bf16 v[16:31], v[244:247], v[218:221], v[16:31]
	ds_read_b128 v[244:247], v154 offset:46080
	v_mfma_f32_32x32x16_bf16 v[32:47], v[248:251], v[214:217], v[32:47]
	v_mfma_f32_32x32x16_bf16 v[0:15], v[248:251], v[218:221], v[0:15]
	ds_read_b128 v[248:251], v154 offset:50688
	v_mfma_f32_32x32x16_bf16 v[112:127], v[222:225], v[214:217], v[112:127]
	v_mfma_f32_32x32x16_bf16 v[80:95], v[222:225], v[218:221], v[80:95]
	s_waitcnt lgkmcnt(3)
	v_mfma_f32_32x32x16_bf16 v[96:111], v[240:243], v[202:205], v[96:111]
	ds_read_b128 v[214:217], v155 offset:36896
	ds_read_b128 v[218:221], v155 offset:41504
	v_mfma_f32_32x32x16_bf16 v[64:79], v[240:243], v[206:209], v[64:79]
	ds_read_b128 v[240:243], v154 offset:41504
	s_waitcnt lgkmcnt(4)
	v_mfma_f32_32x32x16_bf16 v[48:63], v[244:247], v[202:205], v[48:63]
	ds_read_b128 v[222:225], v154 offset:36896
	v_mfma_f32_32x32x16_bf16 v[16:31], v[244:247], v[206:209], v[16:31]
	ds_read_b128 v[244:247], v154 offset:46112
	s_waitcnt lgkmcnt(5)
	v_mfma_f32_32x32x16_bf16 v[32:47], v[248:251], v[202:205], v[32:47]
	s_waitcnt vmcnt(7)
	ds_write_b128 v156, v[170:173] offset:0
	global_load_dwordx4 v[170:173], v[142:143], off offset:896
	v_mfma_f32_32x32x16_bf16 v[0:15], v[248:251], v[206:209], v[0:15]
	ds_read_b128 v[248:251], v154 offset:50720
	s_waitcnt vmcnt(7)
	ds_write_b128 v156, v[178:181] offset:9216
	global_load_dwordx4 v[178:181], v[146:147], off offset:896
	v_mfma_f32_32x32x16_bf16 v[112:127], v[210:213], v[202:205], v[112:127]
	s_waitcnt vmcnt(7)
	ds_write_b128 v156, v[186:189] offset:18432
	global_load_dwordx4 v[186:189], v[148:149], off offset:896
	v_mfma_f32_32x32x16_bf16 v[80:95], v[210:213], v[206:209], v[80:95]
	s_waitcnt vmcnt(7)
	ds_write_b128 v156, v[194:197] offset:27648
	global_load_dwordx4 v[194:197], v[150:151], off offset:896
	s_waitcnt lgkmcnt(7)
	v_mfma_f32_32x32x16_bf16 v[96:111], v[240:243], v[214:217], v[96:111]
	ds_read_b128 v[202:205], v155 offset:36928
	ds_read_b128 v[206:209], v155 offset:41536
	v_mfma_f32_32x32x16_bf16 v[64:79], v[240:243], v[218:221], v[64:79]
	ds_read_b128 v[240:243], v154 offset:41536
	s_waitcnt lgkmcnt(8)
	v_mfma_f32_32x32x16_bf16 v[48:63], v[244:247], v[214:217], v[48:63]
	ds_read_b128 v[210:213], v154 offset:36928
	v_mfma_f32_32x32x16_bf16 v[16:31], v[244:247], v[218:221], v[16:31]
	ds_read_b128 v[244:247], v154 offset:46144
	s_waitcnt lgkmcnt(8)
	v_mfma_f32_32x32x16_bf16 v[32:47], v[248:251], v[214:217], v[32:47]
	s_waitcnt vmcnt(7)
	ds_write_b128 v157, v[174:177] offset:0
	global_load_dwordx4 v[174:177], v[136:137], off offset:896
	v_mfma_f32_32x32x16_bf16 v[0:15], v[248:251], v[218:221], v[0:15]
	ds_read_b128 v[248:251], v154 offset:50752
	s_waitcnt vmcnt(7)
	ds_write_b128 v157, v[182:185] offset:9216
	global_load_dwordx4 v[182:185], v[138:139], off offset:896
	v_mfma_f32_32x32x16_bf16 v[112:127], v[222:225], v[214:217], v[112:127]
	s_waitcnt vmcnt(7)
	ds_write_b128 v157, v[190:193] offset:18432
	global_load_dwordx4 v[190:193], v[140:141], off offset:896
	v_mfma_f32_32x32x16_bf16 v[80:95], v[222:225], v[218:221], v[80:95]
	s_waitcnt vmcnt(7)
	ds_write_b128 v157, v[198:201] offset:27648
	global_load_dwordx4 v[198:201], v[144:145], off offset:896
	s_waitcnt lgkmcnt(7)
	v_mfma_f32_32x32x16_bf16 v[96:111], v[240:243], v[202:205], v[96:111]
	ds_read_b128 v[214:217], v155 offset:36960
	ds_read_b128 v[218:221], v155 offset:41568
	v_mfma_f32_32x32x16_bf16 v[64:79], v[240:243], v[206:209], v[64:79]
	ds_read_b128 v[240:243], v154 offset:41568
	s_waitcnt lgkmcnt(8)
	v_mfma_f32_32x32x16_bf16 v[48:63], v[244:247], v[202:205], v[48:63]
	ds_read_b128 v[222:225], v154 offset:36960
	v_mfma_f32_32x32x16_bf16 v[16:31], v[244:247], v[206:209], v[16:31]
	ds_read_b128 v[244:247], v154 offset:46176
	s_waitcnt lgkmcnt(8)
	v_mfma_f32_32x32x16_bf16 v[32:47], v[248:251], v[202:205], v[32:47]
	v_mfma_f32_32x32x16_bf16 v[0:15], v[248:251], v[206:209], v[0:15]
	ds_read_b128 v[248:251], v154 offset:50784
	v_mfma_f32_32x32x16_bf16 v[112:127], v[210:213], v[202:205], v[112:127]
	v_mfma_f32_32x32x16_bf16 v[80:95], v[210:213], v[206:209], v[80:95]
	s_waitcnt lgkmcnt(0)
	s_barrier
; template <class Epi>
; DI void gemm_phase(const bf16_t* A, const bf16_t* Bt, int K, int mtiles, int ntiles, const Epi& epi, char* smem) {
;     ...
;         for (int kt = 0; kt < nk; ++kt) {
;             const int cur = kt & 1;
;             const bf16_t* a_ = sA + cur * 256 * 72 + (wr * 128 + r) * 72 + 8 * h;
;             const bf16_t* b_ = sB + cur * 256 * 72 + (wc * 64 + r) * 72 + 8 * h;
;             bf16_t* wa = sA + (cur ^ 1) * 256 * 72 + srow * 72 + skc; bf16_t* wb = sB + (cur ^ 1) * 256 * 72 + srow * 72 + skc;
;     ...
;             GEMM_KS(0) GEMM_KS(1)
;             __builtin_amdgcn_sched_barrier(0);
;             if (kt + 1 < nk) {
; #pragma unroll
;                 for (int i = 0; i < 4; ++i) *(u32x4*)(wa + 64 * i * 72) = ra[i];
;             }
;             if (kt + 2 < nk) {
; #pragma unroll
;                 for (int i = 0; i < 4; ++i) ra[i] = *(const u32x4*)(Ag + (size_t)(64 * i) * K + (kt + 2) * 64);
;             }
;             GEMM_KS(2)
;             __builtin_amdgcn_sched_barrier(0);
;             if (kt + 1 < nk) {
; #pragma unroll
;                 for (int i = 0; i < 4; ++i) *(u32x4*)(wb + 64 * i * 72) = rb[i];
;             }
;             if (kt + 2 < nk) {
; #pragma unroll
;                 for (int i = 0; i < 4; ++i) rb[i] = *(const u32x4*)(Bg + (size_t)(64 * i) * K + (kt + 2) * 64);
;             }
;             GEMM_KS(3)
;     ...
;             __syncthreads();
	v_mfma_f32_32x32x16_bf16 v[96:111], v[240:243], v[214:217], v[96:111]
	ds_read_b128 v[202:205], v155
	ds_read_b128 v[206:209], v155 offset:4608
	v_mfma_f32_32x32x16_bf16 v[64:79], v[240:243], v[218:221], v[64:79]
	ds_read_b128 v[240:243], v154 offset:4608
	v_mfma_f32_32x32x16_bf16 v[48:63], v[244:247], v[214:217], v[48:63]
	ds_read_b128 v[210:213], v154
	v_mfma_f32_32x32x16_bf16 v[16:31], v[244:247], v[218:221], v[16:31]
	ds_read_b128 v[244:247], v154 offset:9216
	v_mfma_f32_32x32x16_bf16 v[32:47], v[248:251], v[214:217], v[32:47]
	v_mfma_f32_32x32x16_bf16 v[0:15], v[248:251], v[218:221], v[0:15]
	ds_read_b128 v[248:251], v154 offset:13824
	v_mfma_f32_32x32x16_bf16 v[112:127], v[222:225], v[214:217], v[112:127]
	v_mfma_f32_32x32x16_bf16 v[80:95], v[222:225], v[218:221], v[80:95]
	s_waitcnt lgkmcnt(3)
	v_mfma_f32_32x32x16_bf16 v[96:111], v[240:243], v[202:205], v[96:111]
	ds_read_b128 v[214:217], v155 offset:32
	ds_read_b128 v[218:221], v155 offset:4640
	v_mfma_f32_32x32x16_bf16 v[64:79], v[240:243], v[206:209], v[64:79]
	ds_read_b128 v[240:243], v154 offset:4640
	s_waitcnt lgkmcnt(4)
	v_mfma_f32_32x32x16_bf16 v[48:63], v[244:247], v[202:205], v[48:63]
	ds_read_b128 v[222:225], v154 offset:32
	v_mfma_f32_32x32x16_bf16 v[16:31], v[244:247], v[206:209], v[16:31]
	ds_read_b128 v[244:247], v154 offset:9248
	s_waitcnt lgkmcnt(5)
	v_mfma_f32_32x32x16_bf16 v[32:47], v[248:251], v[202:205], v[32:47]
	s_waitcnt vmcnt(7)
	ds_write_b128 v156, v[170:173] offset:36864
	global_load_dwordx4 v[170:173], v[142:143], off offset:1024
	v_mfma_f32_32x32x16_bf16 v[0:15], v[248:251], v[206:209], v[0:15]
	ds_read_b128 v[248:251], v154 offset:13856
	s_waitcnt vmcnt(7)
	ds_write_b128 v156, v[178:181] offset:46080
	global_load_dwordx4 v[178:181], v[146:147], off offset:1024
	v_mfma_f32_32x32x16_bf16 v[112:127], v[210:213], v[202:205], v[112:127]
	s_waitcnt vmcnt(7)
	ds_write_b128 v156, v[186:189] offset:55296
	global_load_dwordx4 v[186:189], v[148:149], off offset:1024
	v_mfma_f32_32x32x16_bf16 v[80:95], v[210:213], v[206:209], v[80:95]
	s_waitcnt vmcnt(7)
	ds_write_b128 v156, v[194:197] offset:64512
	global_load_dwordx4 v[194:197], v[150:151], off offset:1024
	s_waitcnt lgkmcnt(7)
	v_mfma_f32_32x32x16_bf16 v[96:111], v[240:243], v[214:217], v[96:111]
	ds_read_b128 v[202:205], v155 offset:64
	ds_read_b128 v[206:209], v155 offset:4672
	v_mfma_f32_32x32x16_bf16 v[64:79], v[240:243], v[218:221], v[64:79]
	ds_read_b128 v[240:243], v154 offset:4672
	s_waitcnt lgkmcnt(8)
	v_mfma_f32_32x32x16_bf16 v[48:63], v[244:247], v[214:217], v[48:63]
	ds_read_b128 v[210:213], v154 offset:64
	v_mfma_f32_32x32x16_bf16 v[16:31], v[244:247], v[218:221], v[16:31]
	ds_read_b128 v[244:247], v154 offset:9280
	s_waitcnt lgkmcnt(8)
	v_mfma_f32_32x32x16_bf16 v[32:47], v[248:251], v[214:217], v[32:47]
	s_waitcnt vmcnt(7)
	ds_write_b128 v157, v[174:177] offset:36864
	global_load_dwordx4 v[174:177], v[136:137], off offset:1024
	v_mfma_f32_32x32x16_bf16 v[0:15], v[248:251], v[218:221], v[0:15]
	ds_read_b128 v[248:251], v154 offset:13888
	s_waitcnt vmcnt(7)
	ds_write_b128 v157, v[182:185] offset:46080
	global_load_dwordx4 v[182:185], v[138:139], off offset:1024
	v_mfma_f32_32x32x16_bf16 v[112:127], v[222:225], v[214:217], v[112:127]
	s_waitcnt vmcnt(7)
	ds_write_b128 v157, v[190:193] offset:55296
	global_load_dwordx4 v[190:193], v[140:141], off offset:1024
	v_mfma_f32_32x32x16_bf16 v[80:95], v[222:225], v[218:221], v[80:95]
	s_waitcnt vmcnt(7)
	ds_write_b128 v157, v[198:201] offset:64512
	global_load_dwordx4 v[198:201], v[144:145], off offset:1024
	s_waitcnt lgkmcnt(7)
	v_mfma_f32_32x32x16_bf16 v[96:111], v[240:243], v[202:205], v[96:111]
	ds_read_b128 v[214:217], v155 offset:96
	ds_read_b128 v[218:221], v155 offset:4704
	v_mfma_f32_32x32x16_bf16 v[64:79], v[240:243], v[206:209], v[64:79]
	ds_read_b128 v[240:243], v154 offset:4704
	s_waitcnt lgkmcnt(8)
	v_mfma_f32_32x32x16_bf16 v[48:63], v[244:247], v[202:205], v[48:63]
	ds_read_b128 v[222:225], v154 offset:96
	v_mfma_f32_32x32x16_bf16 v[16:31], v[244:247], v[206:209], v[16:31]
	ds_read_b128 v[244:247], v154 offset:9312
	s_waitcnt lgkmcnt(8)
	v_mfma_f32_32x32x16_bf16 v[32:47], v[248:251], v[202:205], v[32:47]
	v_mfma_f32_32x32x16_bf16 v[0:15], v[248:251], v[206:209], v[0:15]
	ds_read_b128 v[248:251], v154 offset:13920
	v_mfma_f32_32x32x16_bf16 v[112:127], v[210:213], v[202:205], v[112:127]
	v_mfma_f32_32x32x16_bf16 v[80:95], v[210:213], v[206:209], v[80:95]
	s_waitcnt lgkmcnt(0)
	s_barrier
; template <class Epi>
; DI void gemm_phase(const bf16_t* A, const bf16_t* Bt, int K, int mtiles, int ntiles, const Epi& epi, char* smem) {
;     ...
;         for (int kt = 0; kt < nk; ++kt) {
;             const int cur = kt & 1;
;             const bf16_t* a_ = sA + cur * 256 * 72 + (wr * 128 + r) * 72 + 8 * h;
;             const bf16_t* b_ = sB + cur * 256 * 72 + (wc * 64 + r) * 72 + 8 * h;
;             bf16_t* wa = sA + (cur ^ 1) * 256 * 72 + srow * 72 + skc; bf16_t* wb = sB + (cur ^ 1) * 256 * 72 + srow * 72 + skc;
;     ...
;             GEMM_KS(0) GEMM_KS(1)
;             __builtin_amdgcn_sched_barrier(0);
;             if (kt + 1 < nk) {
; #pragma unroll
;                 for (int i = 0; i < 4; ++i) *(u32x4*)(wa + 64 * i * 72) = ra[i];
;             }
;             if (kt + 2 < nk) {
; #pragma unroll
;                 for (int i = 0; i < 4; ++i) ra[i] = *(const u32x4*)(Ag + (size_t)(64 * i) * K + (kt + 2) * 64);
;             }
;             GEMM_KS(2)
;             __builtin_amdgcn_sched_barrier(0);
;             if (kt + 1 < nk) {
; #pragma unroll
;                 for (int i = 0; i < 4; ++i) *(u32x4*)(wb + 64 * i * 72) = rb[i];
;             }
;             if (kt + 2 < nk) {
; #pragma unroll
;                 for (int i = 0; i < 4; ++i) rb[i] = *(const u32x4*)(Bg + (size_t)(64 * i) * K + (kt + 2) * 64);
;             }
;             GEMM_KS(3)
;     ...
;             __syncthreads();
	v_mfma_f32_32x32x16_bf16 v[96:111], v[240:243], v[214:217], v[96:111]
	ds_read_b128 v[202:205], v155 offset:36864
	ds_read_b128 v[206:209], v155 offset:41472
	v_mfma_f32_32x32x16_bf16 v[64:79], v[240:243], v[218:221], v[64:79]
	ds_read_b128 v[240:243], v154 offset:41472
	v_mfma_f32_32x32x16_bf16 v[48:63], v[244:247], v[214:217], v[48:63]
	ds_read_b128 v[210:213], v154 offset:36864
	v_mfma_f32_32x32x16_bf16 v[16:31], v[244:247], v[218:221], v[16:31]
	ds_read_b128 v[244:247], v154 offset:46080
	v_mfma_f32_32x32x16_bf16 v[32:47], v[248:251], v[214:217], v[32:47]
	v_mfma_f32_32x32x16_bf16 v[0:15], v[248:251], v[218:221], v[0:15]
	ds_read_b128 v[248:251], v154 offset:50688
	v_mfma_f32_32x32x16_bf16 v[112:127], v[222:225], v[214:217], v[112:127]
	v_mfma_f32_32x32x16_bf16 v[80:95], v[222:225], v[218:221], v[80:95]
	s_waitcnt lgkmcnt(3)
	v_mfma_f32_32x32x16_bf16 v[96:111], v[240:243], v[202:205], v[96:111]
	ds_read_b128 v[214:217], v155 offset:36896
	ds_read_b128 v[218:221], v155 offset:41504
	v_mfma_f32_32x32x16_bf16 v[64:79], v[240:243], v[206:209], v[64:79]
	ds_read_b128 v[240:243], v154 offset:41504
	s_waitcnt lgkmcnt(4)
	v_mfma_f32_32x32x16_bf16 v[48:63], v[244:247], v[202:205], v[48:63]
	ds_read_b128 v[222:225], v154 offset:36896
	v_mfma_f32_32x32x16_bf16 v[16:31], v[244:247], v[206:209], v[16:31]
	ds_read_b128 v[244:247], v154 offset:46112
	s_waitcnt lgkmcnt(5)
	v_mfma_f32_32x32x16_bf16 v[32:47], v[248:251], v[202:205], v[32:47]
	s_waitcnt vmcnt(7)
	ds_write_b128 v156, v[170:173] offset:0
	global_load_dwordx4 v[170:173], v[142:143], off offset:1152
	v_mfma_f32_32x32x16_bf16 v[0:15], v[248:251], v[206:209], v[0:15]
	ds_read_b128 v[248:251], v154 offset:50720
	s_waitcnt vmcnt(7)
	ds_write_b128 v156, v[178:181] offset:9216
	global_load_dwordx4 v[178:181], v[146:147], off offset:1152
	v_mfma_f32_32x32x16_bf16 v[112:127], v[210:213], v[202:205], v[112:127]
	s_waitcnt vmcnt(7)
	ds_write_b128 v156, v[186:189] offset:18432
	global_load_dwordx4 v[186:189], v[148:149], off offset:1152
	v_mfma_f32_32x32x16_bf16 v[80:95], v[210:213], v[206:209], v[80:95]
	s_waitcnt vmcnt(7)
	ds_write_b128 v156, v[194:197] offset:27648
	global_load_dwordx4 v[194:197], v[150:151], off offset:1152
	s_waitcnt lgkmcnt(7)
	v_mfma_f32_32x32x16_bf16 v[96:111], v[240:243], v[214:217], v[96:111]
	ds_read_b128 v[202:205], v155 offset:36928
	ds_read_b128 v[206:209], v155 offset:41536
	v_mfma_f32_32x32x16_bf16 v[64:79], v[240:243], v[218:221], v[64:79]
	ds_read_b128 v[240:243], v154 offset:41536
	s_waitcnt lgkmcnt(8)
	v_mfma_f32_32x32x16_bf16 v[48:63], v[244:247], v[214:217], v[48:63]
	ds_read_b128 v[210:213], v154 offset:36928
	v_mfma_f32_32x32x16_bf16 v[16:31], v[244:247], v[218:221], v[16:31]
	ds_read_b128 v[244:247], v154 offset:46144
	s_waitcnt lgkmcnt(8)
	v_mfma_f32_32x32x16_bf16 v[32:47], v[248:251], v[214:217], v[32:47]
	s_waitcnt vmcnt(7)
	ds_write_b128 v157, v[174:177] offset:0
	global_load_dwordx4 v[174:177], v[136:137], off offset:1152
	v_mfma_f32_32x32x16_bf16 v[0:15], v[248:251], v[218:221], v[0:15]
	ds_read_b128 v[248:251], v154 offset:50752
	s_waitcnt vmcnt(7)
	ds_write_b128 v157, v[182:185] offset:9216
	global_load_dwordx4 v[182:185], v[138:139], off offset:1152
	v_mfma_f32_32x32x16_bf16 v[112:127], v[222:225], v[214:217], v[112:127]
	s_waitcnt vmcnt(7)
	ds_write_b128 v157, v[190:193] offset:18432
	global_load_dwordx4 v[190:193], v[140:141], off offset:1152
	v_mfma_f32_32x32x16_bf16 v[80:95], v[222:225], v[218:221], v[80:95]
	s_waitcnt vmcnt(7)
	ds_write_b128 v157, v[198:201] offset:27648
	global_load_dwordx4 v[198:201], v[144:145], off offset:1152
	s_waitcnt lgkmcnt(7)
	v_mfma_f32_32x32x16_bf16 v[96:111], v[240:243], v[202:205], v[96:111]
	ds_read_b128 v[214:217], v155 offset:36960
	ds_read_b128 v[218:221], v155 offset:41568
	v_mfma_f32_32x32x16_bf16 v[64:79], v[240:243], v[206:209], v[64:79]
	ds_read_b128 v[240:243], v154 offset:41568
	s_waitcnt lgkmcnt(8)
	v_mfma_f32_32x32x16_bf16 v[48:63], v[244:247], v[202:205], v[48:63]
	ds_read_b128 v[222:225], v154 offset:36960
	v_mfma_f32_32x32x16_bf16 v[16:31], v[244:247], v[206:209], v[16:31]
	ds_read_b128 v[244:247], v154 offset:46176
	s_waitcnt lgkmcnt(8)
	v_mfma_f32_32x32x16_bf16 v[32:47], v[248:251], v[202:205], v[32:47]
	v_mfma_f32_32x32x16_bf16 v[0:15], v[248:251], v[206:209], v[0:15]
	ds_read_b128 v[248:251], v154 offset:50784
	v_mfma_f32_32x32x16_bf16 v[112:127], v[210:213], v[202:205], v[112:127]
	v_mfma_f32_32x32x16_bf16 v[80:95], v[210:213], v[206:209], v[80:95]
	s_waitcnt lgkmcnt(0)
	s_barrier
; template <class Epi>
; DI void gemm_phase(const bf16_t* A, const bf16_t* Bt, int K, int mtiles, int ntiles, const Epi& epi, char* smem) {
;     ...
;         for (int kt = 0; kt < nk; ++kt) {
;             const int cur = kt & 1;
;             const bf16_t* a_ = sA + cur * 256 * 72 + (wr * 128 + r) * 72 + 8 * h;
;             const bf16_t* b_ = sB + cur * 256 * 72 + (wc * 64 + r) * 72 + 8 * h;
;             bf16_t* wa = sA + (cur ^ 1) * 256 * 72 + srow * 72 + skc; bf16_t* wb = sB + (cur ^ 1) * 256 * 72 + srow * 72 + skc;
;     ...
;             GEMM_KS(0) GEMM_KS(1)
;             __builtin_amdgcn_sched_barrier(0);
;             if (kt + 1 < nk) {
; #pragma unroll
;                 for (int i = 0; i < 4; ++i) *(u32x4*)(wa + 64 * i * 72) = ra[i];
;             }
;             if (kt + 2 < nk) {
; #pragma unroll
;                 for (int i = 0; i < 4; ++i) ra[i] = *(const u32x4*)(Ag + (size_t)(64 * i) * K + (kt + 2) * 64);
;             }
;             GEMM_KS(2)
;             __builtin_amdgcn_sched_barrier(0);
;             if (kt + 1 < nk) {
; #pragma unroll
;                 for (int i = 0; i < 4; ++i) *(u32x4*)(wb + 64 * i * 72) = rb[i];
;             }
;             if (kt + 2 < nk) {
; #pragma unroll
;                 for (int i = 0; i < 4; ++i) rb[i] = *(const u32x4*)(Bg + (size_t)(64 * i) * K + (kt + 2) * 64);
;             }
;             GEMM_KS(3)
;     ...
;             __syncthreads();
	v_mfma_f32_32x32x16_bf16 v[96:111], v[240:243], v[214:217], v[96:111]
	ds_read_b128 v[202:205], v155
	ds_read_b128 v[206:209], v155 offset:4608
	v_mfma_f32_32x32x16_bf16 v[64:79], v[240:243], v[218:221], v[64:79]
	ds_read_b128 v[240:243], v154 offset:4608
	v_mfma_f32_32x32x16_bf16 v[48:63], v[244:247], v[214:217], v[48:63]
	ds_read_b128 v[210:213], v154
	v_mfma_f32_32x32x16_bf16 v[16:31], v[244:247], v[218:221], v[16:31]
	ds_read_b128 v[244:247], v154 offset:9216
	v_mfma_f32_32x32x16_bf16 v[32:47], v[248:251], v[214:217], v[32:47]
	v_mfma_f32_32x32x16_bf16 v[0:15], v[248:251], v[218:221], v[0:15]
	ds_read_b128 v[248:251], v154 offset:13824
	v_mfma_f32_32x32x16_bf16 v[112:127], v[222:225], v[214:217], v[112:127]
	v_mfma_f32_32x32x16_bf16 v[80:95], v[222:225], v[218:221], v[80:95]
	s_waitcnt lgkmcnt(3)
	v_mfma_f32_32x32x16_bf16 v[96:111], v[240:243], v[202:205], v[96:111]
	ds_read_b128 v[214:217], v155 offset:32
	ds_read_b128 v[218:221], v155 offset:4640
	v_mfma_f32_32x32x16_bf16 v[64:79], v[240:243], v[206:209], v[64:79]
	ds_read_b128 v[240:243], v154 offset:4640
	s_waitcnt lgkmcnt(4)
	v_mfma_f32_32x32x16_bf16 v[48:63], v[244:247], v[202:205], v[48:63]
	ds_read_b128 v[222:225], v154 offset:32
	v_mfma_f32_32x32x16_bf16 v[16:31], v[244:247], v[206:209], v[16:31]
	ds_read_b128 v[244:247], v154 offset:9248
	s_waitcnt lgkmcnt(5)
	v_mfma_f32_32x32x16_bf16 v[32:47], v[248:251], v[202:205], v[32:47]
	s_waitcnt vmcnt(7)
	ds_write_b128 v156, v[170:173] offset:36864
	global_load_dwordx4 v[170:173], v[142:143], off offset:1280
	v_mfma_f32_32x32x16_bf16 v[0:15], v[248:251], v[206:209], v[0:15]
	ds_read_b128 v[248:251], v154 offset:13856
	s_waitcnt vmcnt(7)
	ds_write_b128 v156, v[178:181] offset:46080
	global_load_dwordx4 v[178:181], v[146:147], off offset:1280
	v_mfma_f32_32x32x16_bf16 v[112:127], v[210:213], v[202:205], v[112:127]
	s_waitcnt vmcnt(7)
	ds_write_b128 v156, v[186:189] offset:55296
	global_load_dwordx4 v[186:189], v[148:149], off offset:1280
	v_mfma_f32_32x32x16_bf16 v[80:95], v[210:213], v[206:209], v[80:95]
	s_waitcnt vmcnt(7)
	ds_write_b128 v156, v[194:197] offset:64512
	global_load_dwordx4 v[194:197], v[150:151], off offset:1280
	s_waitcnt lgkmcnt(7)
	v_mfma_f32_32x32x16_bf16 v[96:111], v[240:243], v[214:217], v[96:111]
	ds_read_b128 v[202:205], v155 offset:64
	ds_read_b128 v[206:209], v155 offset:4672
	v_mfma_f32_32x32x16_bf16 v[64:79], v[240:243], v[218:221], v[64:79]
	ds_read_b128 v[240:243], v154 offset:4672
	s_waitcnt lgkmcnt(8)
	v_mfma_f32_32x32x16_bf16 v[48:63], v[244:247], v[214:217], v[48:63]
	ds_read_b128 v[210:213], v154 offset:64
	v_mfma_f32_32x32x16_bf16 v[16:31], v[244:247], v[218:221], v[16:31]
	ds_read_b128 v[244:247], v154 offset:9280
	s_waitcnt lgkmcnt(8)
	v_mfma_f32_32x32x16_bf16 v[32:47], v[248:251], v[214:217], v[32:47]
	s_waitcnt vmcnt(7)
	ds_write_b128 v157, v[174:177] offset:36864
	global_load_dwordx4 v[174:177], v[136:137], off offset:1280
	v_mfma_f32_32x32x16_bf16 v[0:15], v[248:251], v[218:221], v[0:15]
	ds_read_b128 v[248:251], v154 offset:13888
	s_waitcnt vmcnt(7)
	ds_write_b128 v157, v[182:185] offset:46080
	global_load_dwordx4 v[182:185], v[138:139], off offset:1280
	v_mfma_f32_32x32x16_bf16 v[112:127], v[222:225], v[214:217], v[112:127]
	s_waitcnt vmcnt(7)
	ds_write_b128 v157, v[190:193] offset:55296
	global_load_dwordx4 v[190:193], v[140:141], off offset:1280
	v_mfma_f32_32x32x16_bf16 v[80:95], v[222:225], v[218:221], v[80:95]
	s_waitcnt vmcnt(7)
	ds_write_b128 v157, v[198:201] offset:64512
	global_load_dwordx4 v[198:201], v[144:145], off offset:1280
	s_waitcnt lgkmcnt(7)
	v_mfma_f32_32x32x16_bf16 v[96:111], v[240:243], v[202:205], v[96:111]
	ds_read_b128 v[214:217], v155 offset:96
	ds_read_b128 v[218:221], v155 offset:4704
	v_mfma_f32_32x32x16_bf16 v[64:79], v[240:243], v[206:209], v[64:79]
	ds_read_b128 v[240:243], v154 offset:4704
	s_waitcnt lgkmcnt(8)
	v_mfma_f32_32x32x16_bf16 v[48:63], v[244:247], v[202:205], v[48:63]
	ds_read_b128 v[222:225], v154 offset:96
	v_mfma_f32_32x32x16_bf16 v[16:31], v[244:247], v[206:209], v[16:31]
	ds_read_b128 v[244:247], v154 offset:9312
	s_waitcnt lgkmcnt(8)
	v_mfma_f32_32x32x16_bf16 v[32:47], v[248:251], v[202:205], v[32:47]
	v_mfma_f32_32x32x16_bf16 v[0:15], v[248:251], v[206:209], v[0:15]
	ds_read_b128 v[248:251], v154 offset:13920
	v_mfma_f32_32x32x16_bf16 v[112:127], v[210:213], v[202:205], v[112:127]
	v_mfma_f32_32x32x16_bf16 v[80:95], v[210:213], v[206:209], v[80:95]
	s_waitcnt lgkmcnt(0)
	s_barrier
; template <class Epi>
; DI void gemm_phase(const bf16_t* A, const bf16_t* Bt, int K, int mtiles, int ntiles, const Epi& epi, char* smem) {
;     ...
;         for (int kt = 0; kt < nk; ++kt) {
;             const int cur = kt & 1;
;             const bf16_t* a_ = sA + cur * 256 * 72 + (wr * 128 + r) * 72 + 8 * h;
;             const bf16_t* b_ = sB + cur * 256 * 72 + (wc * 64 + r) * 72 + 8 * h;
;             bf16_t* wa = sA + (cur ^ 1) * 256 * 72 + srow * 72 + skc; bf16_t* wb = sB + (cur ^ 1) * 256 * 72 + srow * 72 + skc;
;     ...
;             GEMM_KS(0) GEMM_KS(1)
;             __builtin_amdgcn_sched_barrier(0);
;             if (kt + 1 < nk) {
; #pragma unroll
;                 for (int i = 0; i < 4; ++i) *(u32x4*)(wa + 64 * i * 72) = ra[i];
;             }
;             if (kt + 2 < nk) {
; #pragma unroll
;                 for (int i = 0; i < 4; ++i) ra[i] = *(const u32x4*)(Ag + (size_t)(64 * i) * K + (kt + 2) * 64);
;             }
;             GEMM_KS(2)
;             __builtin_amdgcn_sched_barrier(0);
;             if (kt + 1 < nk) {
; #pragma unroll
;                 for (int i = 0; i < 4; ++i) *(u32x4*)(wb + 64 * i * 72) = rb[i];
;             }
;             if (kt + 2 < nk) {
; #pragma unroll
;                 for (int i = 0; i < 4; ++i) rb[i] = *(const u32x4*)(Bg + (size_t)(64 * i) * K + (kt + 2) * 64);
;             }
;             GEMM_KS(3)
;     ...
;             __syncthreads();
	v_mfma_f32_32x32x16_bf16 v[96:111], v[240:243], v[214:217], v[96:111]
	ds_read_b128 v[202:205], v155 offset:36864
	ds_read_b128 v[206:209], v155 offset:41472
	v_mfma_f32_32x32x16_bf16 v[64:79], v[240:243], v[218:221], v[64:79]
	ds_read_b128 v[240:243], v154 offset:41472
	v_mfma_f32_32x32x16_bf16 v[48:63], v[244:247], v[214:217], v[48:63]
	ds_read_b128 v[210:213], v154 offset:36864
	v_mfma_f32_32x32x16_bf16 v[16:31], v[244:247], v[218:221], v[16:31]
	ds_read_b128 v[244:247], v154 offset:46080
	v_mfma_f32_32x32x16_bf16 v[32:47], v[248:251], v[214:217], v[32:47]
	v_mfma_f32_32x32x16_bf16 v[0:15], v[248:251], v[218:221], v[0:15]
	ds_read_b128 v[248:251], v154 offset:50688
	v_mfma_f32_32x32x16_bf16 v[112:127], v[222:225], v[214:217], v[112:127]
	v_mfma_f32_32x32x16_bf16 v[80:95], v[222:225], v[218:221], v[80:95]
	s_waitcnt lgkmcnt(3)
	v_mfma_f32_32x32x16_bf16 v[96:111], v[240:243], v[202:205], v[96:111]
	ds_read_b128 v[214:217], v155 offset:36896
	ds_read_b128 v[218:221], v155 offset:41504
	v_mfma_f32_32x32x16_bf16 v[64:79], v[240:243], v[206:209], v[64:79]
	ds_read_b128 v[240:243], v154 offset:41504
	s_waitcnt lgkmcnt(4)
	v_mfma_f32_32x32x16_bf16 v[48:63], v[244:247], v[202:205], v[48:63]
	ds_read_b128 v[222:225], v154 offset:36896
	v_mfma_f32_32x32x16_bf16 v[16:31], v[244:247], v[206:209], v[16:31]
	ds_read_b128 v[244:247], v154 offset:46112
	s_waitcnt lgkmcnt(5)
	v_mfma_f32_32x32x16_bf16 v[32:47], v[248:251], v[202:205], v[32:47]
	s_waitcnt vmcnt(7)
	ds_write_b128 v156, v[170:173] offset:0
	global_load_dwordx4 v[170:173], v[142:143], off offset:1408
	v_mfma_f32_32x32x16_bf16 v[0:15], v[248:251], v[206:209], v[0:15]
	ds_read_b128 v[248:251], v154 offset:50720
	s_waitcnt vmcnt(7)
	ds_write_b128 v156, v[178:181] offset:9216
	global_load_dwordx4 v[178:181], v[146:147], off offset:1408
	v_mfma_f32_32x32x16_bf16 v[112:127], v[210:213], v[202:205], v[112:127]
	s_waitcnt vmcnt(7)
	ds_write_b128 v156, v[186:189] offset:18432
	global_load_dwordx4 v[186:189], v[148:149], off offset:1408
	v_mfma_f32_32x32x16_bf16 v[80:95], v[210:213], v[206:209], v[80:95]
	s_waitcnt vmcnt(7)
	ds_write_b128 v156, v[194:197] offset:27648
	global_load_dwordx4 v[194:197], v[150:151], off offset:1408
	s_waitcnt lgkmcnt(7)
	v_mfma_f32_32x32x16_bf16 v[96:111], v[240:243], v[214:217], v[96:111]
	ds_read_b128 v[202:205], v155 offset:36928
	ds_read_b128 v[206:209], v155 offset:41536
	v_mfma_f32_32x32x16_bf16 v[64:79], v[240:243], v[218:221], v[64:79]
	ds_read_b128 v[240:243], v154 offset:41536
	s_waitcnt lgkmcnt(8)
	v_mfma_f32_32x32x16_bf16 v[48:63], v[244:247], v[214:217], v[48:63]
	ds_read_b128 v[210:213], v154 offset:36928
	v_mfma_f32_32x32x16_bf16 v[16:31], v[244:247], v[218:221], v[16:31]
	ds_read_b128 v[244:247], v154 offset:46144
	s_waitcnt lgkmcnt(8)
	v_mfma_f32_32x32x16_bf16 v[32:47], v[248:251], v[214:217], v[32:47]
	s_waitcnt vmcnt(7)
	ds_write_b128 v157, v[174:177] offset:0
	global_load_dwordx4 v[174:177], v[136:137], off offset:1408
	v_mfma_f32_32x32x16_bf16 v[0:15], v[248:251], v[218:221], v[0:15]
	ds_read_b128 v[248:251], v154 offset:50752
	s_waitcnt vmcnt(7)
	ds_write_b128 v157, v[182:185] offset:9216
	global_load_dwordx4 v[182:185], v[138:139], off offset:1408
	v_mfma_f32_32x32x16_bf16 v[112:127], v[222:225], v[214:217], v[112:127]
	s_waitcnt vmcnt(7)
	ds_write_b128 v157, v[190:193] offset:18432
	global_load_dwordx4 v[190:193], v[140:141], off offset:1408
	v_mfma_f32_32x32x16_bf16 v[80:95], v[222:225], v[218:221], v[80:95]
	s_waitcnt vmcnt(7)
	ds_write_b128 v157, v[198:201] offset:27648
	global_load_dwordx4 v[198:201], v[144:145], off offset:1408
	s_waitcnt lgkmcnt(7)
	v_mfma_f32_32x32x16_bf16 v[96:111], v[240:243], v[202:205], v[96:111]
	ds_read_b128 v[214:217], v155 offset:36960
	ds_read_b128 v[218:221], v155 offset:41568
	v_mfma_f32_32x32x16_bf16 v[64:79], v[240:243], v[206:209], v[64:79]
	ds_read_b128 v[240:243], v154 offset:41568
	s_waitcnt lgkmcnt(8)
	v_mfma_f32_32x32x16_bf16 v[48:63], v[244:247], v[202:205], v[48:63]
	ds_read_b128 v[222:225], v154 offset:36960
	v_mfma_f32_32x32x16_bf16 v[16:31], v[244:247], v[206:209], v[16:31]
	ds_read_b128 v[244:247], v154 offset:46176
	s_waitcnt lgkmcnt(8)
	v_mfma_f32_32x32x16_bf16 v[32:47], v[248:251], v[202:205], v[32:47]
	v_mfma_f32_32x32x16_bf16 v[0:15], v[248:251], v[206:209], v[0:15]
	ds_read_b128 v[248:251], v154 offset:50784
	v_mfma_f32_32x32x16_bf16 v[112:127], v[210:213], v[202:205], v[112:127]
	v_mfma_f32_32x32x16_bf16 v[80:95], v[210:213], v[206:209], v[80:95]
	s_waitcnt lgkmcnt(0)
	s_barrier
; template <class Epi>
; DI void gemm_phase(const bf16_t* A, const bf16_t* Bt, int K, int mtiles, int ntiles, const Epi& epi, char* smem) {
;     ...
;         for (int kt = 0; kt < nk; ++kt) {
;             const int cur = kt & 1;
;             const bf16_t* a_ = sA + cur * 256 * 72 + (wr * 128 + r) * 72 + 8 * h;
;             const bf16_t* b_ = sB + cur * 256 * 72 + (wc * 64 + r) * 72 + 8 * h;
;             bf16_t* wa = sA + (cur ^ 1) * 256 * 72 + srow * 72 + skc; bf16_t* wb = sB + (cur ^ 1) * 256 * 72 + srow * 72 + skc;
;     ...
;             GEMM_KS(0) GEMM_KS(1)
;             __builtin_amdgcn_sched_barrier(0);
;             if (kt + 1 < nk) {
; #pragma unroll
;                 for (int i = 0; i < 4; ++i) *(u32x4*)(wa + 64 * i * 72) = ra[i];
;             }
;             if (kt + 2 < nk) {
; #pragma unroll
;                 for (int i = 0; i < 4; ++i) ra[i] = *(const u32x4*)(Ag + (size_t)(64 * i) * K + (kt + 2) * 64);
;             }
;             GEMM_KS(2)
;             __builtin_amdgcn_sched_barrier(0);
;             if (kt + 1 < nk) {
; #pragma unroll
;                 for (int i = 0; i < 4; ++i) *(u32x4*)(wb + 64 * i * 72) = rb[i];
;             }
;             if (kt + 2 < nk) {
; #pragma unroll
;                 for (int i = 0; i < 4; ++i) rb[i] = *(const u32x4*)(Bg + (size_t)(64 * i) * K + (kt + 2) * 64);
;             }
;             GEMM_KS(3)
;     ...
;             __syncthreads();
	v_mfma_f32_32x32x16_bf16 v[96:111], v[240:243], v[214:217], v[96:111]
	ds_read_b128 v[202:205], v155
	ds_read_b128 v[206:209], v155 offset:4608
	v_mfma_f32_32x32x16_bf16 v[64:79], v[240:243], v[218:221], v[64:79]
	ds_read_b128 v[240:243], v154 offset:4608
	v_mfma_f32_32x32x16_bf16 v[48:63], v[244:247], v[214:217], v[48:63]
	ds_read_b128 v[210:213], v154
	v_mfma_f32_32x32x16_bf16 v[16:31], v[244:247], v[218:221], v[16:31]
	ds_read_b128 v[244:247], v154 offset:9216
	v_mfma_f32_32x32x16_bf16 v[32:47], v[248:251], v[214:217], v[32:47]
	v_mfma_f32_32x32x16_bf16 v[0:15], v[248:251], v[218:221], v[0:15]
	ds_read_b128 v[248:251], v154 offset:13824
	v_mfma_f32_32x32x16_bf16 v[112:127], v[222:225], v[214:217], v[112:127]
	v_mfma_f32_32x32x16_bf16 v[80:95], v[222:225], v[218:221], v[80:95]
	s_waitcnt lgkmcnt(3)
	v_mfma_f32_32x32x16_bf16 v[96:111], v[240:243], v[202:205], v[96:111]
	ds_read_b128 v[214:217], v155 offset:32
	ds_read_b128 v[218:221], v155 offset:4640
	v_mfma_f32_32x32x16_bf16 v[64:79], v[240:243], v[206:209], v[64:79]
	ds_read_b128 v[240:243], v154 offset:4640
	s_waitcnt lgkmcnt(4)
	v_mfma_f32_32x32x16_bf16 v[48:63], v[244:247], v[202:205], v[48:63]
	ds_read_b128 v[222:225], v154 offset:32
	v_mfma_f32_32x32x16_bf16 v[16:31], v[244:247], v[206:209], v[16:31]
	ds_read_b128 v[244:247], v154 offset:9248
	s_waitcnt lgkmcnt(5)
	v_mfma_f32_32x32x16_bf16 v[32:47], v[248:251], v[202:205], v[32:47]
	s_waitcnt vmcnt(7)
	ds_write_b128 v156, v[170:173] offset:36864
	global_load_dwordx4 v[170:173], v[142:143], off offset:1536
	v_mfma_f32_32x32x16_bf16 v[0:15], v[248:251], v[206:209], v[0:15]
	ds_read_b128 v[248:251], v154 offset:13856
	s_waitcnt vmcnt(7)
	ds_write_b128 v156, v[178:181] offset:46080
	global_load_dwordx4 v[178:181], v[146:147], off offset:1536
	v_mfma_f32_32x32x16_bf16 v[112:127], v[210:213], v[202:205], v[112:127]
	s_waitcnt vmcnt(7)
	ds_write_b128 v156, v[186:189] offset:55296
	global_load_dwordx4 v[186:189], v[148:149], off offset:1536
	v_mfma_f32_32x32x16_bf16 v[80:95], v[210:213], v[206:209], v[80:95]
	s_waitcnt vmcnt(7)
	ds_write_b128 v156, v[194:197] offset:64512
	global_load_dwordx4 v[194:197], v[150:151], off offset:1536
	s_waitcnt lgkmcnt(7)
	v_mfma_f32_32x32x16_bf16 v[96:111], v[240:243], v[214:217], v[96:111]
	ds_read_b128 v[202:205], v155 offset:64
	ds_read_b128 v[206:209], v155 offset:4672
	v_mfma_f32_32x32x16_bf16 v[64:79], v[240:243], v[218:221], v[64:79]
	ds_read_b128 v[240:243], v154 offset:4672
	s_waitcnt lgkmcnt(8)
	v_mfma_f32_32x32x16_bf16 v[48:63], v[244:247], v[214:217], v[48:63]
	ds_read_b128 v[210:213], v154 offset:64
	v_mfma_f32_32x32x16_bf16 v[16:31], v[244:247], v[218:221], v[16:31]
	ds_read_b128 v[244:247], v154 offset:9280
	s_waitcnt lgkmcnt(8)
	v_mfma_f32_32x32x16_bf16 v[32:47], v[248:251], v[214:217], v[32:47]
	s_waitcnt vmcnt(7)
	ds_write_b128 v157, v[174:177] offset:36864
	global_load_dwordx4 v[174:177], v[136:137], off offset:1536
	v_mfma_f32_32x32x16_bf16 v[0:15], v[248:251], v[218:221], v[0:15]
	ds_read_b128 v[248:251], v154 offset:13888
	s_waitcnt vmcnt(7)
	ds_write_b128 v157, v[182:185] offset:46080
	global_load_dwordx4 v[182:185], v[138:139], off offset:1536
	v_mfma_f32_32x32x16_bf16 v[112:127], v[222:225], v[214:217], v[112:127]
	s_waitcnt vmcnt(7)
	ds_write_b128 v157, v[190:193] offset:55296
	global_load_dwordx4 v[190:193], v[140:141], off offset:1536
	v_mfma_f32_32x32x16_bf16 v[80:95], v[222:225], v[218:221], v[80:95]
	s_waitcnt vmcnt(7)
	ds_write_b128 v157, v[198:201] offset:64512
	global_load_dwordx4 v[198:201], v[144:145], off offset:1536
	s_waitcnt lgkmcnt(7)
	v_mfma_f32_32x32x16_bf16 v[96:111], v[240:243], v[202:205], v[96:111]
	ds_read_b128 v[214:217], v155 offset:96
	ds_read_b128 v[218:221], v155 offset:4704
	v_mfma_f32_32x32x16_bf16 v[64:79], v[240:243], v[206:209], v[64:79]
	ds_read_b128 v[240:243], v154 offset:4704
	s_waitcnt lgkmcnt(8)
	v_mfma_f32_32x32x16_bf16 v[48:63], v[244:247], v[202:205], v[48:63]
	ds_read_b128 v[222:225], v154 offset:96
	v_mfma_f32_32x32x16_bf16 v[16:31], v[244:247], v[206:209], v[16:31]
	ds_read_b128 v[244:247], v154 offset:9312
	s_waitcnt lgkmcnt(8)
	v_mfma_f32_32x32x16_bf16 v[32:47], v[248:251], v[202:205], v[32:47]
	v_mfma_f32_32x32x16_bf16 v[0:15], v[248:251], v[206:209], v[0:15]
	ds_read_b128 v[248:251], v154 offset:13920
	v_mfma_f32_32x32x16_bf16 v[112:127], v[210:213], v[202:205], v[112:127]
	v_mfma_f32_32x32x16_bf16 v[80:95], v[210:213], v[206:209], v[80:95]
	s_waitcnt lgkmcnt(0)
	s_barrier
; template <class Epi>
; DI void gemm_phase(const bf16_t* A, const bf16_t* Bt, int K, int mtiles, int ntiles, const Epi& epi, char* smem) {
;     ...
;         for (int kt = 0; kt < nk; ++kt) {
;             const int cur = kt & 1;
;             const bf16_t* a_ = sA + cur * 256 * 72 + (wr * 128 + r) * 72 + 8 * h;
;             const bf16_t* b_ = sB + cur * 256 * 72 + (wc * 64 + r) * 72 + 8 * h;
;             bf16_t* wa = sA + (cur ^ 1) * 256 * 72 + srow * 72 + skc; bf16_t* wb = sB + (cur ^ 1) * 256 * 72 + srow * 72 + skc;
;     ...
;             GEMM_KS(0) GEMM_KS(1)
;             __builtin_amdgcn_sched_barrier(0);
;             if (kt + 1 < nk) {
; #pragma unroll
;                 for (int i = 0; i < 4; ++i) *(u32x4*)(wa + 64 * i * 72) = ra[i];
;             }
;             if (kt + 2 < nk) {
; #pragma unroll
;                 for (int i = 0; i < 4; ++i) ra[i] = *(const u32x4*)(Ag + (size_t)(64 * i) * K + (kt + 2) * 64);
;             }
;             GEMM_KS(2)
;             __builtin_amdgcn_sched_barrier(0);
;             if (kt + 1 < nk) {
; #pragma unroll
;                 for (int i = 0; i < 4; ++i) *(u32x4*)(wb + 64 * i * 72) = rb[i];
;             }
;             if (kt + 2 < nk) {
; #pragma unroll
;                 for (int i = 0; i < 4; ++i) rb[i] = *(const u32x4*)(Bg + (size_t)(64 * i) * K + (kt + 2) * 64);
;             }
;             GEMM_KS(3)
;     ...
;             __syncthreads();
;         }
	v_mfma_f32_32x32x16_bf16 v[96:111], v[240:243], v[214:217], v[96:111]
	ds_read_b128 v[202:205], v155 offset:36864
	ds_read_b128 v[206:209], v155 offset:41472
	v_mfma_f32_32x32x16_bf16 v[64:79], v[240:243], v[218:221], v[64:79]
	ds_read_b128 v[240:243], v154 offset:41472
	v_mfma_f32_32x32x16_bf16 v[48:63], v[244:247], v[214:217], v[48:63]
	ds_read_b128 v[210:213], v154 offset:36864
	v_mfma_f32_32x32x16_bf16 v[16:31], v[244:247], v[218:221], v[16:31]
	ds_read_b128 v[244:247], v154 offset:46080
	v_mfma_f32_32x32x16_bf16 v[32:47], v[248:251], v[214:217], v[32:47]
	v_mfma_f32_32x32x16_bf16 v[0:15], v[248:251], v[218:221], v[0:15]
	ds_read_b128 v[248:251], v154 offset:50688
	v_mfma_f32_32x32x16_bf16 v[112:127], v[222:225], v[214:217], v[112:127]
	v_mfma_f32_32x32x16_bf16 v[80:95], v[222:225], v[218:221], v[80:95]
	s_waitcnt lgkmcnt(3)
	v_mfma_f32_32x32x16_bf16 v[96:111], v[240:243], v[202:205], v[96:111]
	ds_read_b128 v[214:217], v155 offset:36896
	ds_read_b128 v[218:221], v155 offset:41504
	v_mfma_f32_32x32x16_bf16 v[64:79], v[240:243], v[206:209], v[64:79]
	ds_read_b128 v[240:243], v154 offset:41504
	s_waitcnt lgkmcnt(4)
	v_mfma_f32_32x32x16_bf16 v[48:63], v[244:247], v[202:205], v[48:63]
	ds_read_b128 v[222:225], v154 offset:36896
	v_mfma_f32_32x32x16_bf16 v[16:31], v[244:247], v[206:209], v[16:31]
	ds_read_b128 v[244:247], v154 offset:46112
	s_waitcnt lgkmcnt(5)
	v_mfma_f32_32x32x16_bf16 v[32:47], v[248:251], v[202:205], v[32:47]
	s_waitcnt vmcnt(7)
	ds_write_b128 v156, v[170:173] offset:0
	global_load_dwordx4 v[170:173], v[142:143], off offset:1664
	v_mfma_f32_32x32x16_bf16 v[0:15], v[248:251], v[206:209], v[0:15]
	ds_read_b128 v[248:251], v154 offset:50720
	s_waitcnt vmcnt(7)
	ds_write_b128 v156, v[178:181] offset:9216
	global_load_dwordx4 v[178:181], v[146:147], off offset:1664
	v_mfma_f32_32x32x16_bf16 v[112:127], v[210:213], v[202:205], v[112:127]
	s_waitcnt vmcnt(7)
	ds_write_b128 v156, v[186:189] offset:18432
	global_load_dwordx4 v[186:189], v[148:149], off offset:1664
	v_mfma_f32_32x32x16_bf16 v[80:95], v[210:213], v[206:209], v[80:95]
	s_waitcnt vmcnt(7)
	ds_write_b128 v156, v[194:197] offset:27648
	global_load_dwordx4 v[194:197], v[150:151], off offset:1664
	s_waitcnt lgkmcnt(7)
	v_mfma_f32_32x32x16_bf16 v[96:111], v[240:243], v[214:217], v[96:111]
	ds_read_b128 v[202:205], v155 offset:36928
	ds_read_b128 v[206:209], v155 offset:41536
	v_mfma_f32_32x32x16_bf16 v[64:79], v[240:243], v[218:221], v[64:79]
	ds_read_b128 v[240:243], v154 offset:41536
	s_waitcnt lgkmcnt(8)
	v_mfma_f32_32x32x16_bf16 v[48:63], v[244:247], v[214:217], v[48:63]
	ds_read_b128 v[210:213], v154 offset:36928
	v_mfma_f32_32x32x16_bf16 v[16:31], v[244:247], v[218:221], v[16:31]
	ds_read_b128 v[244:247], v154 offset:46144
	s_waitcnt lgkmcnt(8)
	v_mfma_f32_32x32x16_bf16 v[32:47], v[248:251], v[214:217], v[32:47]
	s_waitcnt vmcnt(7)
	ds_write_b128 v157, v[174:177] offset:0
	global_load_dwordx4 v[174:177], v[136:137], off offset:1664
	v_mfma_f32_32x32x16_bf16 v[0:15], v[248:251], v[218:221], v[0:15]
	ds_read_b128 v[248:251], v154 offset:50752
	s_waitcnt vmcnt(7)
	ds_write_b128 v157, v[182:185] offset:9216
	global_load_dwordx4 v[182:185], v[138:139], off offset:1664
	v_mfma_f32_32x32x16_bf16 v[112:127], v[222:225], v[214:217], v[112:127]
	s_waitcnt vmcnt(7)
	ds_write_b128 v157, v[190:193] offset:18432
	global_load_dwordx4 v[190:193], v[140:141], off offset:1664
	v_mfma_f32_32x32x16_bf16 v[80:95], v[222:225], v[218:221], v[80:95]
	s_waitcnt vmcnt(7)
	ds_write_b128 v157, v[198:201] offset:27648
	global_load_dwordx4 v[198:201], v[144:145], off offset:1664
	s_waitcnt lgkmcnt(7)
	v_mfma_f32_32x32x16_bf16 v[96:111], v[240:243], v[202:205], v[96:111]
	ds_read_b128 v[214:217], v155 offset:36960
	ds_read_b128 v[218:221], v155 offset:41568
	v_mfma_f32_32x32x16_bf16 v[64:79], v[240:243], v[206:209], v[64:79]
	ds_read_b128 v[240:243], v154 offset:41568
	s_waitcnt lgkmcnt(8)
	v_mfma_f32_32x32x16_bf16 v[48:63], v[244:247], v[202:205], v[48:63]
	ds_read_b128 v[222:225], v154 offset:36960
	v_mfma_f32_32x32x16_bf16 v[16:31], v[244:247], v[206:209], v[16:31]
	ds_read_b128 v[244:247], v154 offset:46176
	s_waitcnt lgkmcnt(8)
	v_mfma_f32_32x32x16_bf16 v[32:47], v[248:251], v[202:205], v[32:47]
	v_mfma_f32_32x32x16_bf16 v[0:15], v[248:251], v[206:209], v[0:15]
	ds_read_b128 v[248:251], v154 offset:50784
	v_mfma_f32_32x32x16_bf16 v[112:127], v[210:213], v[202:205], v[112:127]
	v_mfma_f32_32x32x16_bf16 v[80:95], v[210:213], v[206:209], v[80:95]
	s_waitcnt lgkmcnt(0)
	s_barrier
; template <class Epi>
; DI void gemm_phase(const bf16_t* A, const bf16_t* Bt, int K, int mtiles, int ntiles, const Epi& epi, char* smem) {
;     ...
;         for (int kt = 0; kt < nk; ++kt) {
;             const int cur = kt & 1;
;             const bf16_t* a_ = sA + cur * 256 * 72 + (wr * 128 + r) * 72 + 8 * h;
;             const bf16_t* b_ = sB + cur * 256 * 72 + (wc * 64 + r) * 72 + 8 * h;
;             bf16_t* wa = sA + (cur ^ 1) * 256 * 72 + srow * 72 + skc; bf16_t* wb = sB + (cur ^ 1) * 256 * 72 + srow * 72 + skc;
;     ...
;             GEMM_KS(0) GEMM_KS(1)
;             __builtin_amdgcn_sched_barrier(0);
;             if (kt + 1 < nk) {
; #pragma unroll
;                 for (int i = 0; i < 4; ++i) *(u32x4*)(wa + 64 * i * 72) = ra[i];
;             }
;             if (kt + 2 < nk) {
; #pragma unroll
;                 for (int i = 0; i < 4; ++i) ra[i] = *(const u32x4*)(Ag + (size_t)(64 * i) * K + (kt + 2) * 64);
;             }
;             GEMM_KS(2)
;             __builtin_amdgcn_sched_barrier(0);
;             if (kt + 1 < nk) {
; #pragma unroll
;                 for (int i = 0; i < 4; ++i) *(u32x4*)(wb + 64 * i * 72) = rb[i];
;             }
;             if (kt + 2 < nk) {
; #pragma unroll
;                 for (int i = 0; i < 4; ++i) rb[i] = *(const u32x4*)(Bg + (size_t)(64 * i) * K + (kt + 2) * 64);
;             }
;             GEMM_KS(3)
;     ...
;             __syncthreads();
;         }
	v_mfma_f32_32x32x16_bf16 v[96:111], v[240:243], v[214:217], v[96:111]
	ds_read_b128 v[202:205], v155
	ds_read_b128 v[206:209], v155 offset:4608
	v_mfma_f32_32x32x16_bf16 v[64:79], v[240:243], v[218:221], v[64:79]
	ds_read_b128 v[240:243], v154 offset:4608
	v_mfma_f32_32x32x16_bf16 v[48:63], v[244:247], v[214:217], v[48:63]
	ds_read_b128 v[210:213], v154
	v_mfma_f32_32x32x16_bf16 v[16:31], v[244:247], v[218:221], v[16:31]
	ds_read_b128 v[244:247], v154 offset:9216
	v_mfma_f32_32x32x16_bf16 v[32:47], v[248:251], v[214:217], v[32:47]
	v_mfma_f32_32x32x16_bf16 v[0:15], v[248:251], v[218:221], v[0:15]
	ds_read_b128 v[248:251], v154 offset:13824
	v_mfma_f32_32x32x16_bf16 v[112:127], v[222:225], v[214:217], v[112:127]
	v_mfma_f32_32x32x16_bf16 v[80:95], v[222:225], v[218:221], v[80:95]
	s_waitcnt lgkmcnt(3)
	v_mfma_f32_32x32x16_bf16 v[96:111], v[240:243], v[202:205], v[96:111]
	ds_read_b128 v[214:217], v155 offset:32
	ds_read_b128 v[218:221], v155 offset:4640
	v_mfma_f32_32x32x16_bf16 v[64:79], v[240:243], v[206:209], v[64:79]
	ds_read_b128 v[240:243], v154 offset:4640
	s_waitcnt lgkmcnt(4)
	v_mfma_f32_32x32x16_bf16 v[48:63], v[244:247], v[202:205], v[48:63]
	ds_read_b128 v[222:225], v154 offset:32
	v_mfma_f32_32x32x16_bf16 v[16:31], v[244:247], v[206:209], v[16:31]
	ds_read_b128 v[244:247], v154 offset:9248
	s_waitcnt lgkmcnt(5)
	v_mfma_f32_32x32x16_bf16 v[32:47], v[248:251], v[202:205], v[32:47]
	s_waitcnt vmcnt(7)
	ds_write_b128 v156, v[170:173] offset:36864
	global_load_dwordx4 v[170:173], v[142:143], off offset:1792
	v_mfma_f32_32x32x16_bf16 v[0:15], v[248:251], v[206:209], v[0:15]
	ds_read_b128 v[248:251], v154 offset:13856
	s_waitcnt vmcnt(7)
	ds_write_b128 v156, v[178:181] offset:46080
	global_load_dwordx4 v[178:181], v[146:147], off offset:1792
	v_mfma_f32_32x32x16_bf16 v[112:127], v[210:213], v[202:205], v[112:127]
	s_waitcnt vmcnt(7)
	ds_write_b128 v156, v[186:189] offset:55296
	global_load_dwordx4 v[186:189], v[148:149], off offset:1792
	v_mfma_f32_32x32x16_bf16 v[80:95], v[210:213], v[206:209], v[80:95]
	s_waitcnt vmcnt(7)
	ds_write_b128 v156, v[194:197] offset:64512
	global_load_dwordx4 v[194:197], v[150:151], off offset:1792
	s_waitcnt lgkmcnt(7)
	v_mfma_f32_32x32x16_bf16 v[96:111], v[240:243], v[214:217], v[96:111]
	ds_read_b128 v[202:205], v155 offset:64
	ds_read_b128 v[206:209], v155 offset:4672
	v_mfma_f32_32x32x16_bf16 v[64:79], v[240:243], v[218:221], v[64:79]
	ds_read_b128 v[240:243], v154 offset:4672
	s_waitcnt lgkmcnt(8)
	v_mfma_f32_32x32x16_bf16 v[48:63], v[244:247], v[214:217], v[48:63]
	ds_read_b128 v[210:213], v154 offset:64
	v_mfma_f32_32x32x16_bf16 v[16:31], v[244:247], v[218:221], v[16:31]
	ds_read_b128 v[244:247], v154 offset:9280
	s_waitcnt lgkmcnt(8)
	v_mfma_f32_32x32x16_bf16 v[32:47], v[248:251], v[214:217], v[32:47]
	s_waitcnt vmcnt(7)
	ds_write_b128 v157, v[174:177] offset:36864
	global_load_dwordx4 v[174:177], v[136:137], off offset:1792
	v_mfma_f32_32x32x16_bf16 v[0:15], v[248:251], v[218:221], v[0:15]
	ds_read_b128 v[248:251], v154 offset:13888
	s_waitcnt vmcnt(7)
	ds_write_b128 v157, v[182:185] offset:46080
	global_load_dwordx4 v[182:185], v[138:139], off offset:1792
	v_mfma_f32_32x32x16_bf16 v[112:127], v[222:225], v[214:217], v[112:127]
	s_waitcnt vmcnt(7)
	ds_write_b128 v157, v[190:193] offset:55296
	global_load_dwordx4 v[190:193], v[140:141], off offset:1792
	v_mfma_f32_32x32x16_bf16 v[80:95], v[222:225], v[218:221], v[80:95]
	s_waitcnt vmcnt(7)
	ds_write_b128 v157, v[198:201] offset:64512
	global_load_dwordx4 v[198:201], v[144:145], off offset:1792
	s_waitcnt lgkmcnt(7)
	v_mfma_f32_32x32x16_bf16 v[96:111], v[240:243], v[202:205], v[96:111]
	ds_read_b128 v[214:217], v155 offset:96
	ds_read_b128 v[218:221], v155 offset:4704
	v_mfma_f32_32x32x16_bf16 v[64:79], v[240:243], v[206:209], v[64:79]
	ds_read_b128 v[240:243], v154 offset:4704
	s_waitcnt lgkmcnt(8)
	v_mfma_f32_32x32x16_bf16 v[48:63], v[244:247], v[202:205], v[48:63]
	ds_read_b128 v[222:225], v154 offset:96
	v_mfma_f32_32x32x16_bf16 v[16:31], v[244:247], v[206:209], v[16:31]
	ds_read_b128 v[244:247], v154 offset:9312
	s_waitcnt lgkmcnt(8)
	v_mfma_f32_32x32x16_bf16 v[32:47], v[248:251], v[202:205], v[32:47]
	v_mfma_f32_32x32x16_bf16 v[0:15], v[248:251], v[206:209], v[0:15]
	ds_read_b128 v[248:251], v154 offset:13920
	v_mfma_f32_32x32x16_bf16 v[112:127], v[210:213], v[202:205], v[112:127]
	v_mfma_f32_32x32x16_bf16 v[80:95], v[210:213], v[206:209], v[80:95]
	s_waitcnt lgkmcnt(0)
	s_barrier
; template <class Epi>
; DI void gemm_phase(const bf16_t* A, const bf16_t* Bt, int K, int mtiles, int ntiles, const Epi& epi, char* smem) {
;     ...
;         for (int kt = 0; kt < nk; ++kt) {
;             const int cur = kt & 1;
;             const bf16_t* a_ = sA + cur * 256 * 72 + (wr * 128 + r) * 72 + 8 * h;
;             const bf16_t* b_ = sB + cur * 256 * 72 + (wc * 64 + r) * 72 + 8 * h;
;             bf16_t* wa = sA + (cur ^ 1) * 256 * 72 + srow * 72 + skc; bf16_t* wb = sB + (cur ^ 1) * 256 * 72 + srow * 72 + skc;
;     ...
;             GEMM_KS(0) GEMM_KS(1)
;             __builtin_amdgcn_sched_barrier(0);
;             if (kt + 1 < nk) {
; #pragma unroll
;                 for (int i = 0; i < 4; ++i) *(u32x4*)(wa + 64 * i * 72) = ra[i];
;             }
;             if (kt + 2 < nk) {
; #pragma unroll
;                 for (int i = 0; i < 4; ++i) ra[i] = *(const u32x4*)(Ag + (size_t)(64 * i) * K + (kt + 2) * 64);
;             }
;             GEMM_KS(2)
;             __builtin_amdgcn_sched_barrier(0);
;             if (kt + 1 < nk) {
; #pragma unroll
;                 for (int i = 0; i < 4; ++i) *(u32x4*)(wb + 64 * i * 72) = rb[i];
;             }
;             if (kt + 2 < nk) {
; #pragma unroll
;                 for (int i = 0; i < 4; ++i) rb[i] = *(const u32x4*)(Bg + (size_t)(64 * i) * K + (kt + 2) * 64);
;             }
;             GEMM_KS(3)
;     ...
;             __syncthreads();
;         }
	v_mfma_f32_32x32x16_bf16 v[96:111], v[240:243], v[214:217], v[96:111]
	ds_read_b128 v[202:205], v155 offset:36864
	ds_read_b128 v[206:209], v155 offset:41472
	v_mfma_f32_32x32x16_bf16 v[64:79], v[240:243], v[218:221], v[64:79]
	ds_read_b128 v[240:243], v154 offset:41472
	v_mfma_f32_32x32x16_bf16 v[48:63], v[244:247], v[214:217], v[48:63]
	ds_read_b128 v[210:213], v154 offset:36864
	v_mfma_f32_32x32x16_bf16 v[16:31], v[244:247], v[218:221], v[16:31]
	ds_read_b128 v[244:247], v154 offset:46080
	v_mfma_f32_32x32x16_bf16 v[32:47], v[248:251], v[214:217], v[32:47]
	v_mfma_f32_32x32x16_bf16 v[0:15], v[248:251], v[218:221], v[0:15]
	ds_read_b128 v[248:251], v154 offset:50688
	v_mfma_f32_32x32x16_bf16 v[112:127], v[222:225], v[214:217], v[112:127]
	v_mfma_f32_32x32x16_bf16 v[80:95], v[222:225], v[218:221], v[80:95]
	s_waitcnt lgkmcnt(3)
	v_mfma_f32_32x32x16_bf16 v[96:111], v[240:243], v[202:205], v[96:111]
	ds_read_b128 v[214:217], v155 offset:36896
	ds_read_b128 v[218:221], v155 offset:41504
	v_mfma_f32_32x32x16_bf16 v[64:79], v[240:243], v[206:209], v[64:79]
	ds_read_b128 v[240:243], v154 offset:41504
	s_waitcnt lgkmcnt(4)
	v_mfma_f32_32x32x16_bf16 v[48:63], v[244:247], v[202:205], v[48:63]
	ds_read_b128 v[222:225], v154 offset:36896
	v_mfma_f32_32x32x16_bf16 v[16:31], v[244:247], v[206:209], v[16:31]
	ds_read_b128 v[244:247], v154 offset:46112
	s_waitcnt lgkmcnt(5)
	v_mfma_f32_32x32x16_bf16 v[32:47], v[248:251], v[202:205], v[32:47]
	s_waitcnt vmcnt(7)
	ds_write_b128 v156, v[170:173] offset:0
	global_load_dwordx4 v[170:173], v[142:143], off offset:1920
	v_mfma_f32_32x32x16_bf16 v[0:15], v[248:251], v[206:209], v[0:15]
	ds_read_b128 v[248:251], v154 offset:50720
	s_waitcnt vmcnt(7)
	ds_write_b128 v156, v[178:181] offset:9216
	global_load_dwordx4 v[178:181], v[146:147], off offset:1920
	v_mfma_f32_32x32x16_bf16 v[112:127], v[210:213], v[202:205], v[112:127]
	s_waitcnt vmcnt(7)
	ds_write_b128 v156, v[186:189] offset:18432
	global_load_dwordx4 v[186:189], v[148:149], off offset:1920
	v_mfma_f32_32x32x16_bf16 v[80:95], v[210:213], v[206:209], v[80:95]
	s_waitcnt vmcnt(7)
	ds_write_b128 v156, v[194:197] offset:27648
	global_load_dwordx4 v[194:197], v[150:151], off offset:1920
	s_waitcnt lgkmcnt(7)
	v_mfma_f32_32x32x16_bf16 v[96:111], v[240:243], v[214:217], v[96:111]
	ds_read_b128 v[202:205], v155 offset:36928
	ds_read_b128 v[206:209], v155 offset:41536
	v_mfma_f32_32x32x16_bf16 v[64:79], v[240:243], v[218:221], v[64:79]
	ds_read_b128 v[240:243], v154 offset:41536
	s_waitcnt lgkmcnt(8)
	v_mfma_f32_32x32x16_bf16 v[48:63], v[244:247], v[214:217], v[48:63]
	ds_read_b128 v[210:213], v154 offset:36928
	v_mfma_f32_32x32x16_bf16 v[16:31], v[244:247], v[218:221], v[16:31]
	ds_read_b128 v[244:247], v154 offset:46144
	s_waitcnt lgkmcnt(8)
	v_mfma_f32_32x32x16_bf16 v[32:47], v[248:251], v[214:217], v[32:47]
	s_waitcnt vmcnt(7)
	ds_write_b128 v157, v[174:177] offset:0
	global_load_dwordx4 v[174:177], v[136:137], off offset:1920
	v_mfma_f32_32x32x16_bf16 v[0:15], v[248:251], v[218:221], v[0:15]
	ds_read_b128 v[248:251], v154 offset:50752
	s_waitcnt vmcnt(7)
	ds_write_b128 v157, v[182:185] offset:9216
	global_load_dwordx4 v[182:185], v[138:139], off offset:1920
	v_mfma_f32_32x32x16_bf16 v[112:127], v[222:225], v[214:217], v[112:127]
	s_waitcnt vmcnt(7)
	ds_write_b128 v157, v[190:193] offset:18432
	global_load_dwordx4 v[190:193], v[140:141], off offset:1920
	v_mfma_f32_32x32x16_bf16 v[80:95], v[222:225], v[218:221], v[80:95]
	s_waitcnt vmcnt(7)
	ds_write_b128 v157, v[198:201] offset:27648
	global_load_dwordx4 v[198:201], v[144:145], off offset:1920
	s_waitcnt lgkmcnt(7)
	v_mfma_f32_32x32x16_bf16 v[96:111], v[240:243], v[202:205], v[96:111]
	ds_read_b128 v[214:217], v155 offset:36960
	ds_read_b128 v[218:221], v155 offset:41568
	v_mfma_f32_32x32x16_bf16 v[64:79], v[240:243], v[206:209], v[64:79]
	ds_read_b128 v[240:243], v154 offset:41568
	s_waitcnt lgkmcnt(8)
	v_mfma_f32_32x32x16_bf16 v[48:63], v[244:247], v[202:205], v[48:63]
	ds_read_b128 v[222:225], v154 offset:36960
	v_mfma_f32_32x32x16_bf16 v[16:31], v[244:247], v[206:209], v[16:31]
	ds_read_b128 v[244:247], v154 offset:46176
	s_waitcnt lgkmcnt(8)
	v_mfma_f32_32x32x16_bf16 v[32:47], v[248:251], v[202:205], v[32:47]
	v_mfma_f32_32x32x16_bf16 v[0:15], v[248:251], v[206:209], v[0:15]
	ds_read_b128 v[248:251], v154 offset:50784
	v_mfma_f32_32x32x16_bf16 v[112:127], v[210:213], v[202:205], v[112:127]
	v_mfma_f32_32x32x16_bf16 v[80:95], v[210:213], v[206:209], v[80:95]
	s_waitcnt lgkmcnt(0)
	s_barrier
; template <class Epi>
; DI void gemm_phase(const bf16_t* A, const bf16_t* Bt, int K, int mtiles, int ntiles, const Epi& epi, char* smem) {
;     ...
;         for (int kt = 0; kt < nk; ++kt) {
;             const int cur = kt & 1;
;             const bf16_t* a_ = sA + cur * 256 * 72 + (wr * 128 + r) * 72 + 8 * h;
;             const bf16_t* b_ = sB + cur * 256 * 72 + (wc * 64 + r) * 72 + 8 * h;
;             bf16_t* wa = sA + (cur ^ 1) * 256 * 72 + srow * 72 + skc; bf16_t* wb = sB + (cur ^ 1) * 256 * 72 + srow * 72 + skc;
;     ...
;             GEMM_KS(0) GEMM_KS(1)
;             __builtin_amdgcn_sched_barrier(0);
;             if (kt + 1 < nk) {
; #pragma unroll
;                 for (int i = 0; i < 4; ++i) *(u32x4*)(wa + 64 * i * 72) = ra[i];
;             }
;             if (kt + 2 < nk) {
; #pragma unroll
;                 for (int i = 0; i < 4; ++i) ra[i] = *(const u32x4*)(Ag + (size_t)(64 * i) * K + (kt + 2) * 64);
;             }
;             GEMM_KS(2)
;             __builtin_amdgcn_sched_barrier(0);
;             if (kt + 1 < nk) {
; #pragma unroll
;                 for (int i = 0; i < 4; ++i) *(u32x4*)(wb + 64 * i * 72) = rb[i];
;             }
;             if (kt + 2 < nk) {
; #pragma unroll
;                 for (int i = 0; i < 4; ++i) rb[i] = *(const u32x4*)(Bg + (size_t)(64 * i) * K + (kt + 2) * 64);
;             }
;             GEMM_KS(3)
;     ...
;             __syncthreads();
;         }
	v_mfma_f32_32x32x16_bf16 v[96:111], v[240:243], v[214:217], v[96:111]
	ds_read_b128 v[202:205], v155
	ds_read_b128 v[206:209], v155 offset:4608
	v_mfma_f32_32x32x16_bf16 v[64:79], v[240:243], v[218:221], v[64:79]
	ds_read_b128 v[240:243], v154 offset:4608
	v_mfma_f32_32x32x16_bf16 v[48:63], v[244:247], v[214:217], v[48:63]
	ds_read_b128 v[210:213], v154
	v_mfma_f32_32x32x16_bf16 v[16:31], v[244:247], v[218:221], v[16:31]
	ds_read_b128 v[244:247], v154 offset:9216
	v_mfma_f32_32x32x16_bf16 v[32:47], v[248:251], v[214:217], v[32:47]
	v_mfma_f32_32x32x16_bf16 v[0:15], v[248:251], v[218:221], v[0:15]
	ds_read_b128 v[248:251], v154 offset:13824
	v_mfma_f32_32x32x16_bf16 v[112:127], v[222:225], v[214:217], v[112:127]
	v_mfma_f32_32x32x16_bf16 v[80:95], v[222:225], v[218:221], v[80:95]
	s_waitcnt lgkmcnt(3)
	v_mfma_f32_32x32x16_bf16 v[96:111], v[240:243], v[202:205], v[96:111]
	ds_read_b128 v[214:217], v155 offset:32
	ds_read_b128 v[218:221], v155 offset:4640
	v_mfma_f32_32x32x16_bf16 v[64:79], v[240:243], v[206:209], v[64:79]
	ds_read_b128 v[240:243], v154 offset:4640
	s_waitcnt lgkmcnt(4)
	v_mfma_f32_32x32x16_bf16 v[48:63], v[244:247], v[202:205], v[48:63]
	ds_read_b128 v[222:225], v154 offset:32
	v_mfma_f32_32x32x16_bf16 v[16:31], v[244:247], v[206:209], v[16:31]
	ds_read_b128 v[244:247], v154 offset:9248
	s_waitcnt lgkmcnt(5)
	v_mfma_f32_32x32x16_bf16 v[32:47], v[248:251], v[202:205], v[32:47]
	s_waitcnt vmcnt(7)
	ds_write_b128 v156, v[170:173] offset:36864
	v_mfma_f32_32x32x16_bf16 v[0:15], v[248:251], v[206:209], v[0:15]
	ds_read_b128 v[248:251], v154 offset:13856
	s_waitcnt vmcnt(6)
	ds_write_b128 v156, v[178:181] offset:46080
	v_mfma_f32_32x32x16_bf16 v[112:127], v[210:213], v[202:205], v[112:127]
	s_waitcnt vmcnt(5)
	ds_write_b128 v156, v[186:189] offset:55296
	v_mfma_f32_32x32x16_bf16 v[80:95], v[210:213], v[206:209], v[80:95]
	s_waitcnt vmcnt(4)
	ds_write_b128 v156, v[194:197] offset:64512
	s_waitcnt lgkmcnt(7)
	v_mfma_f32_32x32x16_bf16 v[96:111], v[240:243], v[214:217], v[96:111]
	ds_read_b128 v[202:205], v155 offset:64
	ds_read_b128 v[206:209], v155 offset:4672
	v_mfma_f32_32x32x16_bf16 v[64:79], v[240:243], v[218:221], v[64:79]
	ds_read_b128 v[240:243], v154 offset:4672
	s_waitcnt lgkmcnt(8)
	v_mfma_f32_32x32x16_bf16 v[48:63], v[244:247], v[214:217], v[48:63]
	ds_read_b128 v[210:213], v154 offset:64
	v_mfma_f32_32x32x16_bf16 v[16:31], v[244:247], v[218:221], v[16:31]
	ds_read_b128 v[244:247], v154 offset:9280
	s_waitcnt lgkmcnt(8)
	v_mfma_f32_32x32x16_bf16 v[32:47], v[248:251], v[214:217], v[32:47]
	s_waitcnt vmcnt(3)
	ds_write_b128 v157, v[174:177] offset:36864
	v_mfma_f32_32x32x16_bf16 v[0:15], v[248:251], v[218:221], v[0:15]
	ds_read_b128 v[248:251], v154 offset:13888
	s_waitcnt vmcnt(2)
	ds_write_b128 v157, v[182:185] offset:46080
	v_mfma_f32_32x32x16_bf16 v[112:127], v[222:225], v[214:217], v[112:127]
	s_waitcnt vmcnt(1)
	ds_write_b128 v157, v[190:193] offset:55296
	v_mfma_f32_32x32x16_bf16 v[80:95], v[222:225], v[218:221], v[80:95]
	s_waitcnt vmcnt(0)
	ds_write_b128 v157, v[198:201] offset:64512
	s_waitcnt lgkmcnt(7)
	v_mfma_f32_32x32x16_bf16 v[96:111], v[240:243], v[202:205], v[96:111]
	ds_read_b128 v[214:217], v155 offset:96
	ds_read_b128 v[218:221], v155 offset:4704
	v_mfma_f32_32x32x16_bf16 v[64:79], v[240:243], v[206:209], v[64:79]
	ds_read_b128 v[240:243], v154 offset:4704
	s_waitcnt lgkmcnt(8)
	v_mfma_f32_32x32x16_bf16 v[48:63], v[244:247], v[202:205], v[48:63]
	ds_read_b128 v[222:225], v154 offset:96
	v_mfma_f32_32x32x16_bf16 v[16:31], v[244:247], v[206:209], v[16:31]
	ds_read_b128 v[244:247], v154 offset:9312
	s_waitcnt lgkmcnt(8)
	v_mfma_f32_32x32x16_bf16 v[32:47], v[248:251], v[202:205], v[32:47]
	v_mfma_f32_32x32x16_bf16 v[0:15], v[248:251], v[206:209], v[0:15]
	ds_read_b128 v[248:251], v154 offset:13920
	v_mfma_f32_32x32x16_bf16 v[112:127], v[210:213], v[202:205], v[112:127]
	v_mfma_f32_32x32x16_bf16 v[80:95], v[210:213], v[206:209], v[80:95]
	s_waitcnt lgkmcnt(0)
	s_barrier
	v_mfma_f32_32x32x16_bf16 v[96:111], v[240:243], v[214:217], v[96:111]
	ds_read_b128 v[202:205], v155 offset:36864
	ds_read_b128 v[206:209], v155 offset:41472
	v_mfma_f32_32x32x16_bf16 v[64:79], v[240:243], v[218:221], v[64:79]
	ds_read_b128 v[240:243], v154 offset:41472
	v_mfma_f32_32x32x16_bf16 v[48:63], v[244:247], v[214:217], v[48:63]
	ds_read_b128 v[210:213], v154 offset:36864
	v_mfma_f32_32x32x16_bf16 v[16:31], v[244:247], v[218:221], v[16:31]
	ds_read_b128 v[244:247], v154 offset:46080
	v_mfma_f32_32x32x16_bf16 v[32:47], v[248:251], v[214:217], v[32:47]
	v_mfma_f32_32x32x16_bf16 v[0:15], v[248:251], v[218:221], v[0:15]
	ds_read_b128 v[248:251], v154 offset:50688
	v_mfma_f32_32x32x16_bf16 v[112:127], v[222:225], v[214:217], v[112:127]
	v_mfma_f32_32x32x16_bf16 v[80:95], v[222:225], v[218:221], v[80:95]
	s_waitcnt lgkmcnt(3)
	v_mfma_f32_32x32x16_bf16 v[96:111], v[240:243], v[202:205], v[96:111]
	ds_read_b128 v[214:217], v155 offset:36896
	ds_read_b128 v[218:221], v155 offset:41504
	v_mfma_f32_32x32x16_bf16 v[64:79], v[240:243], v[206:209], v[64:79]
	ds_read_b128 v[240:243], v154 offset:41504
	s_waitcnt lgkmcnt(4)
	v_mfma_f32_32x32x16_bf16 v[48:63], v[244:247], v[202:205], v[48:63]
	ds_read_b128 v[222:225], v154 offset:36896
	v_mfma_f32_32x32x16_bf16 v[16:31], v[244:247], v[206:209], v[16:31]
	ds_read_b128 v[244:247], v154 offset:46112
	s_waitcnt lgkmcnt(5)
	v_mfma_f32_32x32x16_bf16 v[32:47], v[248:251], v[202:205], v[32:47]
	v_mfma_f32_32x32x16_bf16 v[0:15], v[248:251], v[206:209], v[0:15]
	ds_read_b128 v[248:251], v154 offset:50720
	v_mfma_f32_32x32x16_bf16 v[112:127], v[210:213], v[202:205], v[112:127]
	v_mfma_f32_32x32x16_bf16 v[80:95], v[210:213], v[206:209], v[80:95]
	s_waitcnt lgkmcnt(3)
; DI bf16_t to_bf16(float a) { return (bf16_t)(pk_bf16(a, 0.f) & 0xffffu); }
; DI int crow(int i, int h) { return (i & 3) + 8 * (i >> 2) + 4 * h; }
;     DI void operator()(const f32x16 (&acc)[2][2], int row0, int col0, int r, int h, const float*) const {
; #pragma unroll
;         for (int ni = 0; ni < 2; ++ni) {
;             const int cb = col0 + ni * 32, col = cb + r;
;             if (cb < PW) {
; #pragma unroll
;                 for (int mi = 0; mi < 2; ++mi)
; #pragma unroll
;                     for (int i = 0; i < 16; ++i) PROJ[(size_t)(row0 + mi * 32 + crow(i, h)) * PW + col] = to_bf16(acc[mi][ni][i]);
;             } else if (cb == PW && r < 16) {
; template <class Epi>
; DI void gemm_phase(const bf16_t* A, const bf16_t* Bt, int K, int mtiles, int ntiles, const Epi& epi, char* smem) {
;     ...
;             GEMM_KS(2)
;             __builtin_amdgcn_sched_barrier(0);
;             if (kt + 1 < nk) {
; #pragma unroll
;                 for (int i = 0; i < 4; ++i) *(u32x4*)(wb + 64 * i * 72) = rb[i];
;             }
;             if (kt + 2 < nk) {
; #pragma unroll
;                 for (int i = 0; i < 4; ++i) rb[i] = *(const u32x4*)(Bg + (size_t)(64 * i) * K + (kt + 2) * 64);
;             }
;             GEMM_KS(3)
;     ...
;             __syncthreads();
;         }
	v_mfma_f32_32x32x16_bf16 v[96:111], v[240:243], v[214:217], v[96:111]
	ds_read_b128 v[202:205], v155 offset:36928
	ds_read_b128 v[206:209], v155 offset:41536
	v_mfma_f32_32x32x16_bf16 v[64:79], v[240:243], v[218:221], v[64:79]
	ds_read_b128 v[240:243], v154 offset:41536
	s_waitcnt lgkmcnt(4)
	v_mfma_f32_32x32x16_bf16 v[48:63], v[244:247], v[214:217], v[48:63]
	ds_read_b128 v[210:213], v154 offset:36928
	v_mfma_f32_32x32x16_bf16 v[16:31], v[244:247], v[218:221], v[16:31]
	ds_read_b128 v[244:247], v154 offset:46144
	s_waitcnt lgkmcnt(5)
	v_mfma_f32_32x32x16_bf16 v[32:47], v[248:251], v[214:217], v[32:47]
	v_mfma_f32_32x32x16_bf16 v[0:15], v[248:251], v[218:221], v[0:15]
	ds_read_b128 v[248:251], v154 offset:50752
	v_mfma_f32_32x32x16_bf16 v[112:127], v[222:225], v[214:217], v[112:127]
	v_mfma_f32_32x32x16_bf16 v[80:95], v[222:225], v[218:221], v[80:95]
	s_waitcnt lgkmcnt(3)
	v_mfma_f32_32x32x16_bf16 v[96:111], v[240:243], v[202:205], v[96:111]
	ds_read_b128 v[214:217], v155 offset:36960
	ds_read_b128 v[218:221], v155 offset:41568
	v_mfma_f32_32x32x16_bf16 v[64:79], v[240:243], v[206:209], v[64:79]
	ds_read_b128 v[240:243], v154 offset:41568
	s_waitcnt lgkmcnt(4)
	v_mfma_f32_32x32x16_bf16 v[48:63], v[244:247], v[202:205], v[48:63]
	ds_read_b128 v[222:225], v154 offset:36960
	v_mfma_f32_32x32x16_bf16 v[16:31], v[244:247], v[206:209], v[16:31]
	ds_read_b128 v[244:247], v154 offset:46176
	s_waitcnt lgkmcnt(5)
	v_mfma_f32_32x32x16_bf16 v[32:47], v[248:251], v[202:205], v[32:47]
	v_mfma_f32_32x32x16_bf16 v[0:15], v[248:251], v[206:209], v[0:15]
	ds_read_b128 v[248:251], v154 offset:50784
	v_mfma_f32_32x32x16_bf16 v[112:127], v[210:213], v[202:205], v[112:127]
	v_mfma_f32_32x32x16_bf16 v[80:95], v[210:213], v[206:209], v[80:95]
	s_waitcnt lgkmcnt(3)
	v_mfma_f32_32x32x16_bf16 v[96:111], v[240:243], v[214:217], v[96:111]
	v_mfma_f32_32x32x16_bf16 v[64:79], v[240:243], v[218:221], v[64:79]
	s_waitcnt lgkmcnt(1)
	v_mfma_f32_32x32x16_bf16 v[48:63], v[244:247], v[214:217], v[48:63]
	v_mfma_f32_32x32x16_bf16 v[16:31], v[244:247], v[218:221], v[16:31]
	s_waitcnt lgkmcnt(0)
	v_mfma_f32_32x32x16_bf16 v[32:47], v[248:251], v[214:217], v[32:47]
	v_mfma_f32_32x32x16_bf16 v[0:15], v[248:251], v[218:221], v[0:15]
	v_mfma_f32_32x32x16_bf16 v[112:127], v[222:225], v[214:217], v[112:127]
	v_mfma_f32_32x32x16_bf16 v[80:95], v[222:225], v[218:221], v[80:95]
	s_nop 7
	s_nop 7
	s_setprio 0
	v_or_b32_e32 v136, s5, v153
	s_movk_i32 s0, 0x9ff
	v_add_u32_e32 v138, s4, v158
	v_cmp_lt_i32_e64 s[0:1], s0, v136
	s_barrier
	s_and_saveexec_b64 s[4:5], s[0:1]
	s_xor_b64 s[6:7], exec, s[4:5]
	s_cbranch_execz .LBB0_320
	s_movk_i32 s4, 0xa00
	v_cmp_eq_u32_e64 s[4:5], s4, v136
	s_and_b64 s[12:13], s[4:5], vcc
	s_and_saveexec_b64 s[4:5], s[12:13]
	s_cbranch_execz .LBB0_319
	global_load_dword v137, v[132:133], off
	v_ashrrev_i32_e32 v139, 31, v138
	v_lshlrev_b64 v[140:141], 6, v[138:139]
	v_lshl_add_u64 v[140:141], v[134:135], 0, v[140:141]
	s_waitcnt vmcnt(0)
; DI int crow(int i, int h) { return (i & 3) + 8 * (i >> 2) + 4 * h; }
;     DI void operator()(const f32x16 (&acc)[2][2], int row0, int col0, int r, int h, const float*) const {
;     ...
;             } else if (cb == PW && r < 16) {
;                 const float gb = gate_b[r];
; #pragma unroll
;                 for (int mi = 0; mi < 2; ++mi)
; #pragma unroll
;                     for (int i = 0; i < 16; ++i) GATES[(size_t)(row0 + mi * 32 + crow(i, h)) * 16 + r] = acc[mi][ni][i] + gb;
;             }
	v_add_f32_e32 v112, v112, v137
	global_store_dword v[140:141], v112, off
	v_or_b32_e32 v112, 1, v138
	v_add_f32_e32 v139, v113, v137
	v_ashrrev_i32_e32 v113, 31, v112
	v_lshlrev_b64 v[112:113], 6, v[112:113]
	v_lshl_add_u64 v[112:113], v[134:135], 0, v[112:113]
	global_store_dword v[112:113], v139, off
	v_or_b32_e32 v112, 2, v138
	v_ashrrev_i32_e32 v113, 31, v112
	v_lshlrev_b64 v[112:113], 6, v[112:113]
	v_add_f32_e32 v114, v114, v137
	v_lshl_add_u64 v[112:113], v[134:135], 0, v[112:113]
	global_store_dword v[112:113], v114, off
	v_or_b32_e32 v112, 3, v138
	v_ashrrev_i32_e32 v113, 31, v112
	v_lshlrev_b64 v[112:113], 6, v[112:113]
	v_add_f32_e32 v114, v115, v137
	v_lshl_add_u64 v[112:113], v[134:135], 0, v[112:113]
	global_store_dword v[112:113], v114, off
	v_or_b32_e32 v112, 8, v138
	v_ashrrev_i32_e32 v113, 31, v112
	v_lshlrev_b64 v[112:113], 6, v[112:113]
	v_add_f32_e32 v114, v116, v137
	v_lshl_add_u64 v[112:113], v[134:135], 0, v[112:113]
	global_store_dword v[112:113], v114, off
	v_or_b32_e32 v112, 9, v138
	v_ashrrev_i32_e32 v113, 31, v112
	v_lshlrev_b64 v[112:113], 6, v[112:113]
	v_add_f32_e32 v114, v117, v137
	v_lshl_add_u64 v[112:113], v[134:135], 0, v[112:113]
	global_store_dword v[112:113], v114, off
	v_or_b32_e32 v112, 10, v138
	v_ashrrev_i32_e32 v113, 31, v112
	v_lshlrev_b64 v[112:113], 6, v[112:113]
	v_add_f32_e32 v114, v118, v137
	v_lshl_add_u64 v[112:113], v[134:135], 0, v[112:113]
	global_store_dword v[112:113], v114, off
	v_or_b32_e32 v112, 11, v138
	v_ashrrev_i32_e32 v113, 31, v112
	v_lshlrev_b64 v[112:113], 6, v[112:113]
	v_add_f32_e32 v114, v119, v137
	v_lshl_add_u64 v[112:113], v[134:135], 0, v[112:113]
	global_store_dword v[112:113], v114, off
	v_or_b32_e32 v112, 16, v138
	v_ashrrev_i32_e32 v113, 31, v112
	v_lshlrev_b64 v[112:113], 6, v[112:113]
	v_add_f32_e32 v114, v120, v137
	v_lshl_add_u64 v[112:113], v[134:135], 0, v[112:113]
	global_store_dword v[112:113], v114, off
	v_or_b32_e32 v112, 17, v138
	v_ashrrev_i32_e32 v113, 31, v112
	v_lshlrev_b64 v[112:113], 6, v[112:113]
	v_add_f32_e32 v114, v121, v137
	v_lshl_add_u64 v[112:113], v[134:135], 0, v[112:113]
	global_store_dword v[112:113], v114, off
	v_or_b32_e32 v112, 18, v138
	v_ashrrev_i32_e32 v113, 31, v112
	v_lshlrev_b64 v[112:113], 6, v[112:113]
	v_add_f32_e32 v114, v122, v137
	v_lshl_add_u64 v[112:113], v[134:135], 0, v[112:113]
	global_store_dword v[112:113], v114, off
	v_or_b32_e32 v112, 19, v138
	v_ashrrev_i32_e32 v113, 31, v112
	v_lshlrev_b64 v[112:113], 6, v[112:113]
	v_add_f32_e32 v114, v123, v137
	v_lshl_add_u64 v[112:113], v[134:135], 0, v[112:113]
	global_store_dword v[112:113], v114, off
	v_or_b32_e32 v112, 24, v138
	v_ashrrev_i32_e32 v113, 31, v112
	v_lshlrev_b64 v[112:113], 6, v[112:113]
	v_add_f32_e32 v114, v124, v137
	v_lshl_add_u64 v[112:113], v[134:135], 0, v[112:113]
	global_store_dword v[112:113], v114, off
	v_or_b32_e32 v112, 25, v138
	v_ashrrev_i32_e32 v113, 31, v112
	v_lshlrev_b64 v[112:113], 6, v[112:113]
	v_add_f32_e32 v114, v125, v137
	v_lshl_add_u64 v[112:113], v[134:135], 0, v[112:113]
	global_store_dword v[112:113], v114, off
	v_or_b32_e32 v112, 26, v138
	v_ashrrev_i32_e32 v113, 31, v112
	v_lshlrev_b64 v[112:113], 6, v[112:113]
	v_add_f32_e32 v114, v126, v137
	v_lshl_add_u64 v[112:113], v[134:135], 0, v[112:113]
	global_store_dword v[112:113], v114, off
	v_or_b32_e32 v112, 27, v138
	v_ashrrev_i32_e32 v113, 31, v112
	v_lshlrev_b64 v[112:113], 6, v[112:113]
	v_add_f32_e32 v114, v127, v137
	v_lshl_add_u64 v[112:113], v[134:135], 0, v[112:113]
	global_store_dword v[112:113], v114, off
	v_or_b32_e32 v112, 32, v138
	v_ashrrev_i32_e32 v113, 31, v112
	v_lshlrev_b64 v[112:113], 6, v[112:113]
	v_add_f32_e32 v96, v96, v137
	v_lshl_add_u64 v[112:113], v[134:135], 0, v[112:113]
	global_store_dword v[112:113], v96, off
	v_or_b32_e32 v96, 33, v138
	v_add_f32_e32 v112, v97, v137
	v_ashrrev_i32_e32 v97, 31, v96
	v_lshlrev_b64 v[96:97], 6, v[96:97]
	v_lshl_add_u64 v[96:97], v[134:135], 0, v[96:97]
	global_store_dword v[96:97], v112, off
	v_or_b32_e32 v96, 34, v138
	v_ashrrev_i32_e32 v97, 31, v96
	v_lshlrev_b64 v[96:97], 6, v[96:97]
	v_add_f32_e32 v98, v98, v137
	v_lshl_add_u64 v[96:97], v[134:135], 0, v[96:97]
	global_store_dword v[96:97], v98, off
	v_or_b32_e32 v96, 35, v138
	v_ashrrev_i32_e32 v97, 31, v96
	v_lshlrev_b64 v[96:97], 6, v[96:97]
	v_add_f32_e32 v98, v99, v137
	v_lshl_add_u64 v[96:97], v[134:135], 0, v[96:97]
	global_store_dword v[96:97], v98, off
	v_or_b32_e32 v96, 40, v138
	v_ashrrev_i32_e32 v97, 31, v96
	v_lshlrev_b64 v[96:97], 6, v[96:97]
	v_add_f32_e32 v98, v100, v137
	v_lshl_add_u64 v[96:97], v[134:135], 0, v[96:97]
	global_store_dword v[96:97], v98, off
	v_or_b32_e32 v96, 41, v138
	v_ashrrev_i32_e32 v97, 31, v96
	v_lshlrev_b64 v[96:97], 6, v[96:97]
	v_add_f32_e32 v98, v101, v137
	v_lshl_add_u64 v[96:97], v[134:135], 0, v[96:97]
	global_store_dword v[96:97], v98, off
	v_or_b32_e32 v96, 42, v138
	v_ashrrev_i32_e32 v97, 31, v96
	v_lshlrev_b64 v[96:97], 6, v[96:97]
	v_add_f32_e32 v98, v102, v137
	v_lshl_add_u64 v[96:97], v[134:135], 0, v[96:97]
	global_store_dword v[96:97], v98, off
	v_or_b32_e32 v96, 43, v138
	v_ashrrev_i32_e32 v97, 31, v96
	v_lshlrev_b64 v[96:97], 6, v[96:97]
	v_add_f32_e32 v98, v103, v137
	v_lshl_add_u64 v[96:97], v[134:135], 0, v[96:97]
	global_store_dword v[96:97], v98, off
	v_or_b32_e32 v96, 48, v138
	v_ashrrev_i32_e32 v97, 31, v96
	v_lshlrev_b64 v[96:97], 6, v[96:97]
	v_add_f32_e32 v98, v104, v137
	v_lshl_add_u64 v[96:97], v[134:135], 0, v[96:97]
	global_store_dword v[96:97], v98, off
	v_or_b32_e32 v96, 49, v138
	v_ashrrev_i32_e32 v97, 31, v96
	v_lshlrev_b64 v[96:97], 6, v[96:97]
	v_add_f32_e32 v98, v105, v137
	v_lshl_add_u64 v[96:97], v[134:135], 0, v[96:97]
	global_store_dword v[96:97], v98, off
	v_or_b32_e32 v96, 50, v138
	v_ashrrev_i32_e32 v97, 31, v96
	v_lshlrev_b64 v[96:97], 6, v[96:97]
	v_add_f32_e32 v98, v106, v137
	v_lshl_add_u64 v[96:97], v[134:135], 0, v[96:97]
	global_store_dword v[96:97], v98, off
	v_or_b32_e32 v96, 51, v138
	v_ashrrev_i32_e32 v97, 31, v96
	v_lshlrev_b64 v[96:97], 6, v[96:97]
	v_add_f32_e32 v98, v107, v137
	v_lshl_add_u64 v[96:97], v[134:135], 0, v[96:97]
	global_store_dword v[96:97], v98, off
	v_or_b32_e32 v96, 56, v138
	v_ashrrev_i32_e32 v97, 31, v96
	v_lshlrev_b64 v[96:97], 6, v[96:97]
	v_add_f32_e32 v98, v108, v137
	v_lshl_add_u64 v[96:97], v[134:135], 0, v[96:97]
	global_store_dword v[96:97], v98, off
	v_or_b32_e32 v96, 57, v138
	v_ashrrev_i32_e32 v97, 31, v96
	v_lshlrev_b64 v[96:97], 6, v[96:97]
	v_add_f32_e32 v98, v109, v137
	v_lshl_add_u64 v[96:97], v[134:135], 0, v[96:97]
	global_store_dword v[96:97], v98, off
	v_or_b32_e32 v96, 58, v138
	v_ashrrev_i32_e32 v97, 31, v96
	v_lshlrev_b64 v[96:97], 6, v[96:97]
	v_add_f32_e32 v98, v110, v137
	v_lshl_add_u64 v[96:97], v[134:135], 0, v[96:97]
	global_store_dword v[96:97], v98, off
	v_or_b32_e32 v96, 59, v138
	v_ashrrev_i32_e32 v97, 31, v96
	v_lshlrev_b64 v[96:97], 6, v[96:97]
	v_add_f32_e32 v98, v111, v137
	v_lshl_add_u64 v[96:97], v[134:135], 0, v[96:97]
	global_store_dword v[96:97], v98, off
